# out-proj epilogues: residual loads also issued lane-contiguous (8 rows x 64/128B per instruction) and moved to the MFMA layout by ds_bpermute
# baseline (speedup 1.0000x reference)
; #define PG8_STAGE(bufoff, gbase, voff) do { _Pragma("unroll") for (int _i = 0; _i < 2; ++_i) \
;         __builtin_amdgcn_global_load_lds((const unsigned*)((const char*)(gbase) + (voff)[_i]), (LAS unsigned*)(lds + (bufoff) + ldsw + _i * 8192), 16, 0, 0); } while (0)
; #define PG8_LDA(dst, b, h) do { _Pragma("unroll") for (int m = 0; m < 4; ++m) _Pragma("unroll") for (int k = 0; k < 2; ++k) dst[m][k] = *(const LAS bf16x8*)(lds + PG8_SA(b, h) + aoff + m * 2048 + k * 1024); } while (0)
; #define PG8_LDB(dst, b, h) do { _Pragma("unroll") for (int n = 0; n < 2; ++n) _Pragma("unroll") for (int k = 0; k < 2; ++k) dst[n][k] = *(const LAS bf16x8*)(lds + PG8_SB(b, h) + boff + n * 2048 + k * 1024); } while (0)
; #define PG8_MMA(ai, bj, At, Bt) do { __builtin_amdgcn_s_setprio(1); _Pragma("unroll") for (int m = 0; m < 4; ++m) _Pragma("unroll") for (int n = 0; n < 2; ++n) _Pragma("unroll") for (int k = 0; k < 2; ++k) \
;         acc[ai][bj][m][n] = __builtin_amdgcn_mfma_f32_16x16x32_bf16(Bt[n][k], At[m][k], acc[ai][bj][m][n], 0, 0, 0); __builtin_amdgcn_s_setprio(0); } while (0)
; #define PG8_WAIT_L(n) asm volatile("s_waitcnt lgkmcnt(" #n ")" ::: "memory")
; #define PG8_BAR __builtin_amdgcn_s_barrier()
; #define PG8_SCHED __builtin_amdgcn_sched_barrier(0)
; template <class Epi, class Sched>
; DI void gemm_phase(LAS unsigned char* lds, const Gemm g, const Sched& S, const Epi& E) {
;     ...
;             PG8_LDB(B0, 0, 0); PG8_SCHED; PG8_LDA(At, 0, 0); PG8_STAGE(PG8_SA(1, 1), a1 + hstep, voffA);
;             PG8_WAIT_L(8); PG8_BAR; PG8_WAIT_L(0); PG8_MMA(0, 0, At, B0); PG8_BAR; PG8_SCHED;
;             PG8_LDB(B1, 0, 1); PG8_STAGE(PG8_SB(0, 0), b2, voffB);
;             PG8_BAR; PG8_WAIT_L(0); PG8_MMA(0, 1, At, B1); PG8_BAR;
;             PG8_LDA(At, 0, 1); PG8_STAGE(PG8_SA(0, 0), a2, voffA);
;             PG8_BAR; PG8_WAIT_L(0); PG8_MMA(1, 0, At, B0); PG8_BAR; PG8_SCHED;
.LBB0_1007:
	ds_read_b128 v[140:143], v147
	ds_read_b128 v[154:157], v147 offset:1024
	ds_read_b128 v[158:161], v147 offset:2048
	ds_read_b128 v[164:167], v147 offset:3072
	s_add_u32 s24, s22, 0xfffc0080
	s_addc_u32 s25, s23, -1
	s_cmp_eq_u32 s66, 12
	s_cselect_b32 s27, s47, s25
	s_cselect_b32 s26, s53, s24
	s_cselect_b32 s25, s54, s59
	s_cselect_b32 s24, s55, s58
	s_mov_b32 m0, s36
	v_lshl_add_u64 v[150:151], s[22:23], 0, v[136:137]
	ds_read_b128 v[168:171], v148
	ds_read_b128 v[172:175], v148 offset:1024
	ds_read_b128 v[176:179], v148 offset:2048
	ds_read_b128 v[180:183], v148 offset:3072
	ds_read_b128 v[184:187], v148 offset:4096
	ds_read_b128 v[188:191], v148 offset:5120
	ds_read_b128 v[192:195], v148 offset:6144
	ds_read_b128 v[198:201], v148 offset:7168
	global_load_lds_dwordx4 v[150:151], off
	v_lshl_add_u64 v[150:151], s[22:23], 0, v[138:139]
	s_mov_b32 m0, s37
	s_nop 0
	global_load_lds_dwordx4 v[150:151], off
	s_waitcnt lgkmcnt(8)
	s_barrier
	s_waitcnt lgkmcnt(0)
	s_setprio 1
	s_waitcnt lgkmcnt(0)
	v_mfma_f32_16x16x32_bf16 v[126:129], v[140:143], v[168:171], v[126:129]
	v_mfma_f32_16x16x32_bf16 v[122:125], v[158:161], v[168:171], v[122:125]
	v_mfma_f32_16x16x32_bf16 v[114:117], v[140:143], v[176:179], v[114:117]
	v_mfma_f32_16x16x32_bf16 v[106:109], v[158:161], v[176:179], v[106:109]
	v_mfma_f32_16x16x32_bf16 v[98:101], v[140:143], v[184:187], v[98:101]
	v_mfma_f32_16x16x32_bf16 v[90:93], v[158:161], v[184:187], v[90:93]
	v_mfma_f32_16x16x32_bf16 v[82:85], v[140:143], v[192:195], v[82:85]
	v_mfma_f32_16x16x32_bf16 v[74:77], v[158:161], v[192:195], v[74:77]
	v_mfma_f32_16x16x32_bf16 v[126:129], v[154:157], v[172:175], v[126:129]
	v_mfma_f32_16x16x32_bf16 v[122:125], v[164:167], v[172:175], v[122:125]
	v_mfma_f32_16x16x32_bf16 v[114:117], v[154:157], v[180:183], v[114:117]
	v_mfma_f32_16x16x32_bf16 v[106:109], v[164:167], v[180:183], v[106:109]
	v_mfma_f32_16x16x32_bf16 v[98:101], v[154:157], v[188:191], v[98:101]
	v_mfma_f32_16x16x32_bf16 v[90:93], v[164:167], v[188:191], v[90:93]
	v_mfma_f32_16x16x32_bf16 v[82:85], v[154:157], v[198:201], v[82:85]
	v_mfma_f32_16x16x32_bf16 v[74:77], v[164:167], v[198:201], v[74:77]
	s_setprio 0
	s_barrier
	s_mov_b32 m0, s38
	v_lshl_add_u64 v[150:151], s[24:25], 0, v[132:133]
	ds_read_b128 v[202:205], v149
	ds_read_b128 v[206:209], v149 offset:1024
	ds_read_b128 v[210:213], v149 offset:2048
	ds_read_b128 v[214:217], v149 offset:3072
	global_load_lds_dwordx4 v[150:151], off
	v_lshl_add_u64 v[218:219], s[24:25], 0, v[130:131]
	s_mov_b32 m0, s39
	s_nop 0
	global_load_lds_dwordx4 v[218:219], off
	s_barrier
	s_waitcnt lgkmcnt(0)
	s_setprio 1
	s_waitcnt lgkmcnt(0)
	v_mfma_f32_16x16x32_bf16 v[118:121], v[202:205], v[168:171], v[118:121]
	v_mfma_f32_16x16x32_bf16 v[110:113], v[210:213], v[168:171], v[110:113]
	v_mfma_f32_16x16x32_bf16 v[102:105], v[202:205], v[176:179], v[102:105]
	v_mfma_f32_16x16x32_bf16 v[94:97], v[210:213], v[176:179], v[94:97]
	v_mfma_f32_16x16x32_bf16 v[86:89], v[202:205], v[184:187], v[86:89]
	v_mfma_f32_16x16x32_bf16 v[78:81], v[210:213], v[184:187], v[78:81]
	v_mfma_f32_16x16x32_bf16 v[70:73], v[202:205], v[192:195], v[70:73]
	v_mfma_f32_16x16x32_bf16 v[66:69], v[210:213], v[192:195], v[66:69]
	v_mfma_f32_16x16x32_bf16 v[118:121], v[206:209], v[172:175], v[118:121]
	v_mfma_f32_16x16x32_bf16 v[110:113], v[214:217], v[172:175], v[110:113]
	v_mfma_f32_16x16x32_bf16 v[102:105], v[206:209], v[180:183], v[102:105]
	v_mfma_f32_16x16x32_bf16 v[94:97], v[214:217], v[180:183], v[94:97]
	v_mfma_f32_16x16x32_bf16 v[86:89], v[206:209], v[188:191], v[86:89]
	v_mfma_f32_16x16x32_bf16 v[78:81], v[214:217], v[188:191], v[78:81]
	v_mfma_f32_16x16x32_bf16 v[70:73], v[206:209], v[198:201], v[70:73]
	v_mfma_f32_16x16x32_bf16 v[66:69], v[214:217], v[198:201], v[66:69]
	s_setprio 0
	s_mov_b32 m0, s13
	v_lshl_add_u64 v[220:221], s[26:27], 0, v[132:133]
	s_barrier
	ds_read_b128 v[168:171], v148 offset:16384
	ds_read_b128 v[172:175], v148 offset:17408
	ds_read_b128 v[176:179], v148 offset:18432
	ds_read_b128 v[180:183], v148 offset:19456
	ds_read_b128 v[184:187], v148 offset:20480
	ds_read_b128 v[188:191], v148 offset:21504
	ds_read_b128 v[192:195], v148 offset:22528
	ds_read_b128 v[198:201], v148 offset:23552
	global_load_lds_dwordx4 v[220:221], off
	v_lshl_add_u64 v[222:223], s[26:27], 0, v[130:131]
	s_mov_b32 m0, s28
	s_nop 0
	global_load_lds_dwordx4 v[222:223], off
	s_barrier
	s_waitcnt lgkmcnt(0)
	s_setprio 1
	s_waitcnt lgkmcnt(0)
	v_mfma_f32_16x16x32_bf16 v[62:65], v[140:143], v[168:171], v[62:65]
	v_mfma_f32_16x16x32_bf16 v[58:61], v[158:161], v[168:171], v[58:61]
	v_mfma_f32_16x16x32_bf16 v[50:53], v[140:143], v[176:179], v[50:53]
	v_mfma_f32_16x16x32_bf16 v[42:45], v[158:161], v[176:179], v[42:45]
	v_mfma_f32_16x16x32_bf16 v[34:37], v[140:143], v[184:187], v[34:37]
	v_mfma_f32_16x16x32_bf16 v[26:29], v[158:161], v[184:187], v[26:29]
	v_mfma_f32_16x16x32_bf16 v[18:21], v[140:143], v[192:195], v[18:21]
	v_mfma_f32_16x16x32_bf16 v[10:13], v[158:161], v[192:195], v[10:13]
	v_mfma_f32_16x16x32_bf16 v[62:65], v[154:157], v[172:175], v[62:65]
	v_mfma_f32_16x16x32_bf16 v[58:61], v[164:167], v[172:175], v[58:61]
	v_mfma_f32_16x16x32_bf16 v[50:53], v[154:157], v[180:183], v[50:53]
	v_mfma_f32_16x16x32_bf16 v[42:45], v[164:167], v[180:183], v[42:45]
	v_mfma_f32_16x16x32_bf16 v[34:37], v[154:157], v[188:191], v[34:37]
	v_mfma_f32_16x16x32_bf16 v[26:29], v[164:167], v[188:191], v[26:29]
	v_mfma_f32_16x16x32_bf16 v[18:21], v[154:157], v[198:201], v[18:21]
	v_mfma_f32_16x16x32_bf16 v[10:13], v[164:167], v[198:201], v[10:13]
	s_setprio 0
	s_barrier
; #define PG8_STAGE(bufoff, gbase, voff) do { _Pragma("unroll") for (int _i = 0; _i < 2; ++_i) \
;         __builtin_amdgcn_global_load_lds((const unsigned*)((const char*)(gbase) + (voff)[_i]), (LAS unsigned*)(lds + (bufoff) + ldsw + _i * 8192), 16, 0, 0); } while (0)
; #define PG8_LDA(dst, b, h) do { _Pragma("unroll") for (int m = 0; m < 4; ++m) _Pragma("unroll") for (int k = 0; k < 2; ++k) dst[m][k] = *(const LAS bf16x8*)(lds + PG8_SA(b, h) + aoff + m * 2048 + k * 1024); } while (0)
; #define PG8_LDB(dst, b, h) do { _Pragma("unroll") for (int n = 0; n < 2; ++n) _Pragma("unroll") for (int k = 0; k < 2; ++k) dst[n][k] = *(const LAS bf16x8*)(lds + PG8_SB(b, h) + boff + n * 2048 + k * 1024); } while (0)
; #define PG8_MMA(ai, bj, At, Bt) do { __builtin_amdgcn_s_setprio(1); _Pragma("unroll") for (int m = 0; m < 4; ++m) _Pragma("unroll") for (int n = 0; n < 2; ++n) _Pragma("unroll") for (int k = 0; k < 2; ++k) \
;         acc[ai][bj][m][n] = __builtin_amdgcn_mfma_f32_16x16x32_bf16(Bt[n][k], At[m][k], acc[ai][bj][m][n], 0, 0, 0); __builtin_amdgcn_s_setprio(0); } while (0)
; #define PG8_WAIT_V(n) asm volatile("s_waitcnt vmcnt(" #n ")" ::: "memory")
; #define PG8_WAIT_L(n) asm volatile("s_waitcnt lgkmcnt(" #n ")" ::: "memory")
; #define PG8_BAR __builtin_amdgcn_s_barrier()
; #define PG8_SCHED __builtin_amdgcn_sched_barrier(0)
; template <class Epi, class Sched>
; DI void gemm_phase(LAS unsigned char* lds, const Gemm g, const Sched& S, const Epi& E) {
;     ...
;             PG8_STAGE(PG8_SB(0, 1), b2 + hstep, voffB);
;             PG8_WAIT_V(6); PG8_BAR; PG8_MMA(1, 1, At, B1); PG8_BAR;
;             PG8_LDB(B0, 1, 0); PG8_SCHED; PG8_LDA(At, 1, 0); PG8_STAGE(PG8_SA(0, 1), a2 + hstep, voffA);
;             PG8_WAIT_L(8); PG8_BAR; PG8_WAIT_L(0); PG8_MMA(0, 0, At, B0); PG8_BAR; PG8_SCHED;
;             PG8_LDB(B1, 1, 1); PG8_STAGE(PG8_SB(1, 0), b3, voffB);
;             PG8_BAR; PG8_WAIT_L(0); PG8_MMA(0, 1, At, B1); PG8_BAR;
;             PG8_LDA(At, 1, 1); PG8_STAGE(PG8_SA(1, 0), a3, voffA);
;             PG8_BAR; PG8_WAIT_L(0); PG8_MMA(1, 0, At, B0); PG8_BAR; PG8_SCHED;
	s_add_u32 s72, s24, 0x40000
	s_addc_u32 s73, s25, 0
	s_add_i32 s67, s35, s12
	v_lshl_add_u64 v[140:141], s[72:73], 0, v[132:133]
	s_mov_b32 m0, s67
	s_nop 0
	global_load_lds_dwordx4 v[140:141], off
	v_lshl_add_u64 v[140:141], s[72:73], 0, v[130:131]
	s_add_i32 m0, s67, 0x2000
	s_nop 0
	global_load_lds_dwordx4 v[140:141], off
	s_waitcnt vmcnt(6)
	s_barrier
	s_setprio 1
	v_mfma_f32_16x16x32_bf16 v[54:57], v[202:205], v[168:171], v[54:57]
	v_mfma_f32_16x16x32_bf16 v[46:49], v[210:213], v[168:171], v[46:49]
	v_mfma_f32_16x16x32_bf16 v[38:41], v[202:205], v[176:179], v[38:41]
	v_mfma_f32_16x16x32_bf16 v[30:33], v[210:213], v[176:179], v[30:33]
	v_mfma_f32_16x16x32_bf16 v[22:25], v[202:205], v[184:187], v[22:25]
	v_mfma_f32_16x16x32_bf16 v[14:17], v[210:213], v[184:187], v[14:17]
	v_mfma_f32_16x16x32_bf16 v[6:9], v[202:205], v[192:195], v[6:9]
	v_mfma_f32_16x16x32_bf16 v[2:5], v[210:213], v[192:195], v[2:5]
	v_mfma_f32_16x16x32_bf16 v[54:57], v[206:209], v[172:175], v[54:57]
	v_mfma_f32_16x16x32_bf16 v[46:49], v[214:217], v[172:175], v[46:49]
	v_mfma_f32_16x16x32_bf16 v[38:41], v[206:209], v[180:183], v[38:41]
	v_mfma_f32_16x16x32_bf16 v[30:33], v[214:217], v[180:183], v[30:33]
	v_mfma_f32_16x16x32_bf16 v[22:25], v[206:209], v[188:191], v[22:25]
	v_mfma_f32_16x16x32_bf16 v[14:17], v[214:217], v[188:191], v[14:17]
	v_mfma_f32_16x16x32_bf16 v[6:9], v[206:209], v[198:201], v[6:9]
	v_mfma_f32_16x16x32_bf16 v[2:5], v[214:217], v[198:201], v[2:5]
	s_setprio 0
	s_add_i32 s67, 0, 0x18000
	v_add_u32_e32 v134, s67, v145
	s_barrier
	ds_read_b128 v[140:143], v134
	ds_read_b128 v[154:157], v134 offset:1024
	ds_read_b128 v[158:161], v134 offset:2048
	ds_read_b128 v[164:167], v134 offset:3072
	s_add_u32 s26, s26, 0x40000
	s_addc_u32 s27, s27, 0
	s_mov_b32 m0, s29
	v_lshl_add_u64 v[202:203], s[26:27], 0, v[132:133]
	ds_read_b128 v[168:171], v148 offset:32768
	ds_read_b128 v[172:175], v148 offset:33792
	ds_read_b128 v[176:179], v148 offset:34816
	ds_read_b128 v[180:183], v148 offset:35840
	ds_read_b128 v[184:187], v148 offset:36864
	ds_read_b128 v[188:191], v148 offset:37888
	ds_read_b128 v[192:195], v148 offset:38912
	ds_read_b128 v[198:201], v148 offset:39936
	global_load_lds_dwordx4 v[202:203], off
	v_lshl_add_u64 v[202:203], s[26:27], 0, v[130:131]
	s_mov_b32 m0, s30
	s_nop 0
	global_load_lds_dwordx4 v[202:203], off
	s_waitcnt lgkmcnt(8)
	s_barrier
	s_waitcnt lgkmcnt(0)
	s_setprio 1
	s_waitcnt lgkmcnt(0)
	v_mfma_f32_16x16x32_bf16 v[126:129], v[140:143], v[168:171], v[126:129]
	v_mfma_f32_16x16x32_bf16 v[122:125], v[158:161], v[168:171], v[122:125]
	v_mfma_f32_16x16x32_bf16 v[114:117], v[140:143], v[176:179], v[114:117]
	v_mfma_f32_16x16x32_bf16 v[106:109], v[158:161], v[176:179], v[106:109]
	v_mfma_f32_16x16x32_bf16 v[98:101], v[140:143], v[184:187], v[98:101]
	v_mfma_f32_16x16x32_bf16 v[90:93], v[158:161], v[184:187], v[90:93]
	v_mfma_f32_16x16x32_bf16 v[82:85], v[140:143], v[192:195], v[82:85]
	v_mfma_f32_16x16x32_bf16 v[74:77], v[158:161], v[192:195], v[74:77]
	v_mfma_f32_16x16x32_bf16 v[126:129], v[154:157], v[172:175], v[126:129]
	v_mfma_f32_16x16x32_bf16 v[122:125], v[164:167], v[172:175], v[122:125]
	v_mfma_f32_16x16x32_bf16 v[114:117], v[154:157], v[180:183], v[114:117]
	v_mfma_f32_16x16x32_bf16 v[106:109], v[164:167], v[180:183], v[106:109]
	v_mfma_f32_16x16x32_bf16 v[98:101], v[154:157], v[188:191], v[98:101]
	v_mfma_f32_16x16x32_bf16 v[90:93], v[164:167], v[188:191], v[90:93]
	v_mfma_f32_16x16x32_bf16 v[82:85], v[154:157], v[198:201], v[82:85]
	v_mfma_f32_16x16x32_bf16 v[74:77], v[164:167], v[198:201], v[74:77]
	s_setprio 0
	s_barrier
	s_add_i32 s26, 0, 0x1c000
	s_add_i32 s27, s67, s12
	v_add_u32_e32 v134, s26, v145
	v_lshl_add_u64 v[150:151], v[150:151], 0, s[10:11]
	s_mov_b32 m0, s27
	ds_read_b128 v[202:205], v134
	ds_read_b128 v[206:209], v134 offset:1024
	ds_read_b128 v[210:213], v134 offset:2048
	ds_read_b128 v[214:217], v134 offset:3072
	global_load_lds_dwordx4 v[150:151], off
	v_lshl_add_u64 v[150:151], v[218:219], 0, s[10:11]
	s_add_i32 m0, s27, 0x2000
	s_nop 0
	global_load_lds_dwordx4 v[150:151], off
	s_barrier
	s_waitcnt lgkmcnt(0)
	s_setprio 1
	s_waitcnt lgkmcnt(0)
	v_mfma_f32_16x16x32_bf16 v[118:121], v[202:205], v[168:171], v[118:121]
	v_mfma_f32_16x16x32_bf16 v[110:113], v[210:213], v[168:171], v[110:113]
	v_mfma_f32_16x16x32_bf16 v[102:105], v[202:205], v[176:179], v[102:105]
	v_mfma_f32_16x16x32_bf16 v[94:97], v[210:213], v[176:179], v[94:97]
	v_mfma_f32_16x16x32_bf16 v[86:89], v[202:205], v[184:187], v[86:89]
	v_mfma_f32_16x16x32_bf16 v[78:81], v[210:213], v[184:187], v[78:81]
	v_mfma_f32_16x16x32_bf16 v[70:73], v[202:205], v[192:195], v[70:73]
	v_mfma_f32_16x16x32_bf16 v[66:69], v[210:213], v[192:195], v[66:69]
	v_mfma_f32_16x16x32_bf16 v[118:121], v[206:209], v[172:175], v[118:121]
	v_mfma_f32_16x16x32_bf16 v[110:113], v[214:217], v[172:175], v[110:113]
	v_mfma_f32_16x16x32_bf16 v[102:105], v[206:209], v[180:183], v[102:105]
	v_mfma_f32_16x16x32_bf16 v[94:97], v[214:217], v[180:183], v[94:97]
	v_mfma_f32_16x16x32_bf16 v[86:89], v[206:209], v[188:191], v[86:89]
	v_mfma_f32_16x16x32_bf16 v[78:81], v[214:217], v[188:191], v[78:81]
	v_mfma_f32_16x16x32_bf16 v[70:73], v[206:209], v[198:201], v[70:73]
	v_mfma_f32_16x16x32_bf16 v[66:69], v[214:217], v[198:201], v[66:69]
	s_setprio 0
	s_mov_b32 m0, s33
	v_lshl_add_u64 v[150:151], v[220:221], 0, s[10:11]
	s_barrier
	ds_read_b128 v[168:171], v148 offset:49152
	ds_read_b128 v[172:175], v148 offset:50176
	ds_read_b128 v[176:179], v148 offset:51200
	ds_read_b128 v[180:183], v148 offset:52224
	ds_read_b128 v[184:187], v148 offset:53248
	ds_read_b128 v[188:191], v148 offset:54272
	ds_read_b128 v[192:195], v148 offset:55296
	ds_read_b128 v[198:201], v148 offset:56320
	global_load_lds_dwordx4 v[150:151], off
	v_lshl_add_u64 v[150:151], v[222:223], 0, s[10:11]
	s_mov_b32 m0, s34
	s_nop 0
	global_load_lds_dwordx4 v[150:151], off
	s_barrier
; DI float bflo(unsigned u) { return __uint_as_float(u << 16); }
; DI float bfhi(unsigned u) { return __uint_as_float(u & 0xffff0000u); }
; #define PG8_STAGE(bufoff, gbase, voff) do { _Pragma("unroll") for (int _i = 0; _i < 2; ++_i) \
;         __builtin_amdgcn_global_load_lds((const unsigned*)((const char*)(gbase) + (voff)[_i]), (LAS unsigned*)(lds + (bufoff) + ldsw + _i * 8192), 16, 0, 0); } while (0)
; #define PG8_LDA(dst, b, h) do { _Pragma("unroll") for (int m = 0; m < 4; ++m) _Pragma("unroll") for (int k = 0; k < 2; ++k) dst[m][k] = *(const LAS bf16x8*)(lds + PG8_SA(b, h) + aoff + m * 2048 + k * 1024); } while (0)
; #define PG8_LDB(dst, b, h) do { _Pragma("unroll") for (int n = 0; n < 2; ++n) _Pragma("unroll") for (int k = 0; k < 2; ++k) dst[n][k] = *(const LAS bf16x8*)(lds + PG8_SB(b, h) + boff + n * 2048 + k * 1024); } while (0)
; #define PG8_WAIT_V(n) asm volatile("s_waitcnt vmcnt(" #n ")" ::: "memory")
;     DI void operator()(const f32x4 (&acc)[2][2][4][2], const Unit& u, int wr, int wc, int fr, int fq) const {
;         const int row0 = u.pm * BM + wr * 64 + fr, col0 = u.pn * BM + wc * 32 + 4 * fq;
; #pragma unroll
;         for (int ai = 0; ai < 2; ++ai)
; #pragma unroll
;             for (int m = 0; m < 4; ++m) { const size_t o = (size_t)(row0 + ai * HALF + m * 16) * 1024 + col0;
; #pragma unroll
;                 for (int bj = 0; bj < 2; ++bj)
; #pragma unroll
;                     for (int n = 0; n < 2; ++n) { const size_t oo = o + bj * HALF + n * 16; f32x4 rv;
;                         if (RES_BF16) { const u32x2 t = *(const u32x2*)((const bf16_t*)res + oo); rv = (f32x4){bflo(t.x), bfhi(t.x), bflo(t.y), bfhi(t.y)}; }
;                         else rv = *(const f32x4*)((const float*)res + oo);
; template <class Epi, class Sched>
; DI void gemm_phase(LAS unsigned char* lds, const Gemm g, const Sched& S, const Epi& E) {
;     ...
;             PG8_WAIT_L(8); PG8_BAR; PG8_WAIT_L(0); PG8_MMA(0, 0, At, B0); PG8_BAR; PG8_SCHED;
;             PG8_LDB(B1, 1, 1); PG8_STAGE(PG8_SB(1, 0), b3, voffB);
;             PG8_BAR; PG8_WAIT_L(0); PG8_MMA(0, 1, At, B1); PG8_BAR;
;             PG8_LDA(At, 1, 1); PG8_STAGE(PG8_SA(1, 0), a3, voffA);
;             PG8_BAR; PG8_WAIT_L(0); PG8_MMA(1, 0, At, B0); PG8_BAR; PG8_SCHED;
;             PG8_STAGE(PG8_SB(1, 1), b3 + hstep, voffB);
;             PG8_WAIT_V(6); PG8_BAR; PG8_MMA(1, 1, At, B1); PG8_BAR;
	s_waitcnt lgkmcnt(0)
	s_setprio 1
	s_waitcnt lgkmcnt(0)
	v_mfma_f32_16x16x32_bf16 v[62:65], v[140:143], v[168:171], v[62:65]
	v_mfma_f32_16x16x32_bf16 v[58:61], v[158:161], v[168:171], v[58:61]
	v_mfma_f32_16x16x32_bf16 v[50:53], v[140:143], v[176:179], v[50:53]
	v_mfma_f32_16x16x32_bf16 v[42:45], v[158:161], v[176:179], v[42:45]
	v_mfma_f32_16x16x32_bf16 v[34:37], v[140:143], v[184:187], v[34:37]
	v_mfma_f32_16x16x32_bf16 v[26:29], v[158:161], v[184:187], v[26:29]
	v_mfma_f32_16x16x32_bf16 v[18:21], v[140:143], v[192:195], v[18:21]
	v_mfma_f32_16x16x32_bf16 v[10:13], v[158:161], v[192:195], v[10:13]
	v_mfma_f32_16x16x32_bf16 v[62:65], v[154:157], v[172:175], v[62:65]
	v_mfma_f32_16x16x32_bf16 v[58:61], v[164:167], v[172:175], v[58:61]
	v_mfma_f32_16x16x32_bf16 v[50:53], v[154:157], v[180:183], v[50:53]
	v_mfma_f32_16x16x32_bf16 v[42:45], v[164:167], v[180:183], v[42:45]
	v_mfma_f32_16x16x32_bf16 v[34:37], v[154:157], v[188:191], v[34:37]
	v_mfma_f32_16x16x32_bf16 v[26:29], v[164:167], v[188:191], v[26:29]
	v_mfma_f32_16x16x32_bf16 v[18:21], v[154:157], v[198:201], v[18:21]
	v_mfma_f32_16x16x32_bf16 v[10:13], v[164:167], v[198:201], v[10:13]
	s_setprio 0
	s_barrier
	s_add_u32 s24, s24, 0x40080
	s_addc_u32 s25, s25, 0
	s_add_i32 s26, s26, s12
	v_lshl_add_u64 v[140:141], s[24:25], 0, v[132:133]
	s_mov_b32 m0, s26
	s_nop 0
	global_load_lds_dwordx4 v[140:141], off
	v_lshl_add_u64 v[140:141], s[24:25], 0, v[130:131]
	s_add_i32 m0, s26, 0x2000
	s_nop 0
	global_load_lds_dwordx4 v[140:141], off
	s_waitcnt vmcnt(6)
	s_barrier
	s_setprio 1
	v_mfma_f32_16x16x32_bf16 v[54:57], v[202:205], v[168:171], v[54:57]
	v_mfma_f32_16x16x32_bf16 v[46:49], v[210:213], v[168:171], v[46:49]
	v_mfma_f32_16x16x32_bf16 v[38:41], v[202:205], v[176:179], v[38:41]
	v_mfma_f32_16x16x32_bf16 v[30:33], v[210:213], v[176:179], v[30:33]
	v_mfma_f32_16x16x32_bf16 v[22:25], v[202:205], v[184:187], v[22:25]
	v_mfma_f32_16x16x32_bf16 v[14:17], v[210:213], v[184:187], v[14:17]
	v_mfma_f32_16x16x32_bf16 v[6:9], v[202:205], v[192:195], v[6:9]
	v_mfma_f32_16x16x32_bf16 v[2:5], v[210:213], v[192:195], v[2:5]
	v_mfma_f32_16x16x32_bf16 v[54:57], v[206:209], v[172:175], v[54:57]
	v_mfma_f32_16x16x32_bf16 v[46:49], v[214:217], v[172:175], v[46:49]
	v_mfma_f32_16x16x32_bf16 v[38:41], v[206:209], v[180:183], v[38:41]
	v_mfma_f32_16x16x32_bf16 v[30:33], v[214:217], v[180:183], v[30:33]
	v_mfma_f32_16x16x32_bf16 v[22:25], v[206:209], v[188:191], v[22:25]
	v_mfma_f32_16x16x32_bf16 v[14:17], v[214:217], v[188:191], v[14:17]
	v_mfma_f32_16x16x32_bf16 v[6:9], v[206:209], v[198:201], v[6:9]
	v_mfma_f32_16x16x32_bf16 v[2:5], v[214:217], v[198:201], v[2:5]
	s_setprio 0
	s_add_i32 s66, s66, 2
	s_add_u32 s22, s22, 0x100
	s_addc_u32 s23, s23, 0
	s_add_u32 s58, s58, 0x100
	s_addc_u32 s59, s59, 0
	s_cmp_gt_u32 s66, 13
	s_barrier
	s_cbranch_scc0 .LBB0_1007
	v_lshl_add_u32 v224, s43, 8, v144
	v_lshl_or_b32 v243, s42, 8, v146
	v_lshl_or_b32 v224, v224, 10, v243
	v_lshlrev_b32_e32 v225, 2, v224
	v_lshlrev_b32_e32 v233, 1, v224
	v_add_u32_e32 v234, 0x4000, v224
	v_lshlrev_b32_e32 v226, 2, v234
	v_lshlrev_b32_e32 v234, 1, v234
	v_add_u32_e32 v235, 0x8000, v224
	v_lshlrev_b32_e32 v227, 2, v235
	v_lshlrev_b32_e32 v235, 1, v235
	v_add_u32_e32 v236, 0xc000, v224
	v_lshlrev_b32_e32 v228, 2, v236
	v_lshlrev_b32_e32 v236, 1, v236
	v_add_u32_e32 v237, 0x20000, v224
	v_lshlrev_b32_e32 v229, 2, v237
	v_lshlrev_b32_e32 v237, 1, v237
	v_add_u32_e32 v240, 0x24000, v224
	v_lshlrev_b32_e32 v230, 2, v240
	v_lshlrev_b32_e32 v240, 1, v240
	v_add_u32_e32 v241, 0x28000, v224
	v_lshlrev_b32_e32 v231, 2, v241
	v_lshlrev_b32_e32 v241, 1, v241
	v_add_u32_e32 v242, 0x2c000, v224
	v_lshlrev_b32_e32 v232, 2, v242
	v_lshlrev_b32_e32 v242, 1, v242
	v_and_b32_e32 v248, 63, v1
	v_lshrrev_b32_e32 v249, 3, v248
	v_and_b32_e32 v250, 3, v248
	v_lshl_or_b32 v250, v250, 4, v249
	v_lshlrev_b32_e32 v244, 2, v250
	v_add_u32_e32 v245, 32, v244
	v_and_b32_e32 v250, 0xffffffc0, v144
	v_add_u32_e32 v250, v250, v249
	v_lshl_add_u32 v250, s43, 8, v250
	v_mul_u32_u24_e32 v250, 0x800, v250
	v_and_b32_e32 v247, 0xffffffe0, v146
	v_lshl_or_b32 v247, s42, 8, v247
	v_lshlrev_b32_e32 v247, 1, v247
	v_and_b32_e32 v248, 7, v248
	v_lshl_add_u32 v247, v248, 3, v247
	v_add_u32_e32 v246, v250, v247
	s_mov_b32 s98, 0xf0f0f0f0
	s_mov_b32 s99, 0xf0f0f0f0
	v_and_b32_e32 v253, 63, v1
	v_and_b32_e32 v254, 7, v253
	v_lshrrev_b32_e32 v253, 4, v253
	v_lshl_or_b32 v253, v254, 3, v253
	v_lshlrev_b32_e32 v253, 2, v253
	v_add_u32_e32 v254, 16, v253
	s_mov_b32 vcc_lo, 0xff00ff00
	s_mov_b32 vcc_hi, 0xff00ff00
	v_lshlrev_b32_e32 v255, 1, v246
	v_mov_b32_e32 v251, v255
	global_load_dwordx4 v[140:143], v251, s[60:61]
	global_load_dwordx4 v[158:161], v251, s[60:61] offset:512
	v_add_u32_e32 v252, 0x8000, v255
	global_load_dwordx4 v[154:157], v252, s[60:61]
	global_load_dwordx4 v[164:167], v252, s[60:61] offset:512
	v_add_u32_e32 v251, 0x10000, v255
	global_load_dwordx4 v[168:171], v251, s[60:61]
	global_load_dwordx4 v[176:179], v251, s[60:61] offset:512
	v_add_u32_e32 v252, 0x18000, v255
	global_load_dwordx4 v[172:175], v252, s[60:61]
	global_load_dwordx4 v[180:183], v252, s[60:61] offset:512
	v_add_u32_e32 v251, 0x20000, v255
	global_load_dwordx4 v[184:187], v251, s[60:61]
	global_load_dwordx4 v[192:195], v251, s[60:61] offset:512
	v_add_u32_e32 v252, 0x28000, v255
	global_load_dwordx4 v[188:191], v252, s[60:61]
	global_load_dwordx4 v[198:201], v252, s[60:61] offset:512
	v_add_u32_e32 v251, 0x30000, v255
	global_load_dwordx4 v[202:205], v251, s[60:61]
	global_load_dwordx4 v[210:213], v251, s[60:61] offset:512
	v_add_u32_e32 v252, 0x38000, v255
	global_load_dwordx4 v[206:209], v252, s[60:61]
	global_load_dwordx4 v[214:217], v252, s[60:61] offset:512
	s_waitcnt vmcnt(12)
; DI unsigned pk_bf16(float a, float b) { f32x2 v = {a, b}; bf2_t r = __builtin_convertvector(v, bf2_t); return __builtin_bit_cast(unsigned, r); }
; DI float bflo(unsigned u) { return __uint_as_float(u << 16); }
; DI float bfhi(unsigned u) { return __uint_as_float(u & 0xffff0000u); }
;     DI void operator()(const f32x4 (&acc)[2][2][4][2], const Unit& u, int wr, int wc, int fr, int fq) const {
;         const int row0 = u.pm * BM + wr * 64 + fr, col0 = u.pn * BM + wc * 32 + 4 * fq;
; #pragma unroll
;         for (int ai = 0; ai < 2; ++ai)
; #pragma unroll
;             for (int m = 0; m < 4; ++m) { const size_t o = (size_t)(row0 + ai * HALF + m * 16) * 1024 + col0;
; #pragma unroll
;                 for (int bj = 0; bj < 2; ++bj)
; #pragma unroll
;                     for (int n = 0; n < 2; ++n) { const size_t oo = o + bj * HALF + n * 16; f32x4 rv;
;                         if (RES_BF16) { const u32x2 t = *(const u32x2*)((const bf16_t*)res + oo); rv = (f32x4){bflo(t.x), bfhi(t.x), bflo(t.y), bfhi(t.y)}; }
;                         else rv = *(const f32x4*)((const float*)res + oo);
;                         const f32x4 v = acc[ai][bj][m][n] + rv; u32x2 w; w.x = pk_bf16(v.x, v.y); w.y = pk_bf16(v.z, v.w);
;                         *(u32x2*)(O + oo) = w; } }
	ds_bpermute_b32 v229, v254, v140
	ds_bpermute_b32 v230, v254, v141
	ds_bpermute_b32 v231, v254, v142
	ds_bpermute_b32 v232, v254, v143
	ds_bpermute_b32 v225, v253, v154
	ds_bpermute_b32 v226, v253, v155
	ds_bpermute_b32 v227, v253, v156
	ds_bpermute_b32 v228, v253, v157
	ds_bpermute_b32 v140, v253, v140
	ds_bpermute_b32 v141, v253, v141
	ds_bpermute_b32 v142, v253, v142
	ds_bpermute_b32 v143, v253, v143
	ds_bpermute_b32 v154, v254, v154
	ds_bpermute_b32 v155, v254, v155
	ds_bpermute_b32 v156, v254, v156
	ds_bpermute_b32 v157, v254, v157
	s_waitcnt lgkmcnt(0)
	v_cndmask_b32_e32 v140, v140, v225, vcc
	v_cndmask_b32_e32 v141, v141, v226, vcc
	v_cndmask_b32_e32 v142, v142, v227, vcc
	v_cndmask_b32_e32 v143, v143, v228, vcc
	v_cndmask_b32_e32 v154, v229, v154, vcc
	v_cndmask_b32_e32 v155, v230, v155, vcc
	v_cndmask_b32_e32 v156, v231, v156, vcc
	v_cndmask_b32_e32 v157, v232, v157, vcc
	ds_bpermute_b32 v237, v254, v158
	ds_bpermute_b32 v240, v254, v159
	ds_bpermute_b32 v241, v254, v160
	ds_bpermute_b32 v242, v254, v161
	ds_bpermute_b32 v233, v253, v164
	ds_bpermute_b32 v234, v253, v165
	ds_bpermute_b32 v235, v253, v166
	ds_bpermute_b32 v236, v253, v167
	ds_bpermute_b32 v158, v253, v158
	ds_bpermute_b32 v159, v253, v159
	ds_bpermute_b32 v160, v253, v160
	ds_bpermute_b32 v161, v253, v161
	ds_bpermute_b32 v164, v254, v164
	ds_bpermute_b32 v165, v254, v165
	ds_bpermute_b32 v166, v254, v166
	ds_bpermute_b32 v167, v254, v167
	s_waitcnt lgkmcnt(0)
	v_cndmask_b32_e32 v158, v158, v233, vcc
	v_cndmask_b32_e32 v159, v159, v234, vcc
	v_cndmask_b32_e32 v160, v160, v235, vcc
	v_cndmask_b32_e32 v161, v161, v236, vcc
	v_cndmask_b32_e32 v164, v237, v164, vcc
	v_cndmask_b32_e32 v165, v240, v165, vcc
	v_cndmask_b32_e32 v166, v241, v166, vcc
	v_cndmask_b32_e32 v167, v242, v167, vcc
	v_pk_add_f32 v[128:129], v[128:129], v[142:143]
	v_pk_add_f32 v[126:127], v[126:127], v[140:141]
	v_pk_add_f32 v[124:125], v[124:125], v[156:157]
	v_pk_add_f32 v[122:123], v[122:123], v[154:155]
	v_pk_add_f32 v[120:121], v[120:121], v[160:161]
	v_pk_add_f32 v[118:119], v[118:119], v[158:159]
	v_pk_add_f32 v[112:113], v[112:113], v[166:167]
	v_pk_add_f32 v[110:111], v[110:111], v[164:165]
	v_cvt_pk_bf16_f32 v126, v126, v127
	v_cvt_pk_bf16_f32 v127, v128, v129
	v_cvt_pk_bf16_f32 v122, v122, v123
	v_cvt_pk_bf16_f32 v123, v124, v125
	v_cvt_pk_bf16_f32 v118, v118, v119
	v_cvt_pk_bf16_f32 v119, v120, v121
	v_cvt_pk_bf16_f32 v110, v110, v111
	v_cvt_pk_bf16_f32 v111, v112, v113
	ds_bpermute_b32 v140, v244, v126
	ds_bpermute_b32 v141, v244, v127
	ds_bpermute_b32 v142, v244, v122
	ds_bpermute_b32 v143, v244, v123
	ds_bpermute_b32 v154, v245, v126
	ds_bpermute_b32 v155, v245, v127
	ds_bpermute_b32 v156, v245, v122
	ds_bpermute_b32 v157, v245, v123
	s_waitcnt lgkmcnt(0)
	v_cndmask_b32_e64 v140, v140, v142, s[98:99]
	v_cndmask_b32_e64 v141, v141, v143, s[98:99]
	v_mov_b32_e32 v142, v246
	global_store_dwordx2 v142, v[140:141], s[48:49]
	v_cndmask_b32_e64 v154, v154, v156, s[98:99]
	v_cndmask_b32_e64 v155, v155, v157, s[98:99]
	v_add_u32_e32 v156, 0x4000, v246
	global_store_dwordx2 v156, v[154:155], s[48:49]
	ds_bpermute_b32 v140, v244, v118
	ds_bpermute_b32 v141, v244, v119
	ds_bpermute_b32 v142, v244, v110
	ds_bpermute_b32 v143, v244, v111
	ds_bpermute_b32 v154, v245, v118
	ds_bpermute_b32 v155, v245, v119
	ds_bpermute_b32 v156, v245, v110
	ds_bpermute_b32 v157, v245, v111
	s_waitcnt lgkmcnt(0)
	v_cndmask_b32_e64 v140, v140, v142, s[98:99]
	v_cndmask_b32_e64 v141, v141, v143, s[98:99]
	v_mov_b32_e32 v142, v246
	global_store_dwordx2 v142, v[140:141], s[48:49] offset:256
	v_cndmask_b32_e64 v154, v154, v156, s[98:99]
	v_cndmask_b32_e64 v155, v155, v157, s[98:99]
	v_add_u32_e32 v156, 0x4000, v246
	global_store_dwordx2 v156, v[154:155], s[48:49] offset:256
	v_add_u32_e32 v251, 0x80000, v255
	global_load_dwordx4 v[140:143], v251, s[60:61]
	global_load_dwordx4 v[158:161], v251, s[60:61] offset:512
	v_add_u32_e32 v252, 0x88000, v255
	global_load_dwordx4 v[154:157], v252, s[60:61]
	global_load_dwordx4 v[164:167], v252, s[60:61] offset:512
	s_waitcnt vmcnt(16)
	ds_bpermute_b32 v229, v254, v168
	ds_bpermute_b32 v230, v254, v169
	ds_bpermute_b32 v231, v254, v170
	ds_bpermute_b32 v232, v254, v171
	ds_bpermute_b32 v225, v253, v172
	ds_bpermute_b32 v226, v253, v173
	ds_bpermute_b32 v227, v253, v174
	ds_bpermute_b32 v228, v253, v175
	ds_bpermute_b32 v168, v253, v168
	ds_bpermute_b32 v169, v253, v169
	ds_bpermute_b32 v170, v253, v170
	ds_bpermute_b32 v171, v253, v171
	ds_bpermute_b32 v172, v254, v172
	ds_bpermute_b32 v173, v254, v173
	ds_bpermute_b32 v174, v254, v174
	ds_bpermute_b32 v175, v254, v175
	s_waitcnt lgkmcnt(0)
	v_cndmask_b32_e32 v168, v168, v225, vcc
	v_cndmask_b32_e32 v169, v169, v226, vcc
	v_cndmask_b32_e32 v170, v170, v227, vcc
	v_cndmask_b32_e32 v171, v171, v228, vcc
	v_cndmask_b32_e32 v172, v229, v172, vcc
	v_cndmask_b32_e32 v173, v230, v173, vcc
	v_cndmask_b32_e32 v174, v231, v174, vcc
	v_cndmask_b32_e32 v175, v232, v175, vcc
	ds_bpermute_b32 v237, v254, v176
	ds_bpermute_b32 v240, v254, v177
	ds_bpermute_b32 v241, v254, v178
	ds_bpermute_b32 v242, v254, v179
	ds_bpermute_b32 v233, v253, v180
	ds_bpermute_b32 v234, v253, v181
	ds_bpermute_b32 v235, v253, v182
	ds_bpermute_b32 v236, v253, v183
	ds_bpermute_b32 v176, v253, v176
	ds_bpermute_b32 v177, v253, v177
	ds_bpermute_b32 v178, v253, v178
	ds_bpermute_b32 v179, v253, v179
	ds_bpermute_b32 v180, v254, v180
	ds_bpermute_b32 v181, v254, v181
	ds_bpermute_b32 v182, v254, v182
	ds_bpermute_b32 v183, v254, v183
	s_waitcnt lgkmcnt(0)
; DI unsigned pk_bf16(float a, float b) { f32x2 v = {a, b}; bf2_t r = __builtin_convertvector(v, bf2_t); return __builtin_bit_cast(unsigned, r); }
; DI float bflo(unsigned u) { return __uint_as_float(u << 16); }
; DI float bfhi(unsigned u) { return __uint_as_float(u & 0xffff0000u); }
;     DI void operator()(const f32x4 (&acc)[2][2][4][2], const Unit& u, int wr, int wc, int fr, int fq) const {
;         const int row0 = u.pm * BM + wr * 64 + fr, col0 = u.pn * BM + wc * 32 + 4 * fq;
; #pragma unroll
;         for (int ai = 0; ai < 2; ++ai)
; #pragma unroll
;             for (int m = 0; m < 4; ++m) { const size_t o = (size_t)(row0 + ai * HALF + m * 16) * 1024 + col0;
; #pragma unroll
;                 for (int bj = 0; bj < 2; ++bj)
; #pragma unroll
;                     for (int n = 0; n < 2; ++n) { const size_t oo = o + bj * HALF + n * 16; f32x4 rv;
;                         if (RES_BF16) { const u32x2 t = *(const u32x2*)((const bf16_t*)res + oo); rv = (f32x4){bflo(t.x), bfhi(t.x), bflo(t.y), bfhi(t.y)}; }
;                         else rv = *(const f32x4*)((const float*)res + oo);
;                         const f32x4 v = acc[ai][bj][m][n] + rv; u32x2 w; w.x = pk_bf16(v.x, v.y); w.y = pk_bf16(v.z, v.w);
;                         *(u32x2*)(O + oo) = w; } }
	v_cndmask_b32_e32 v176, v176, v233, vcc
	v_cndmask_b32_e32 v177, v177, v234, vcc
	v_cndmask_b32_e32 v178, v178, v235, vcc
	v_cndmask_b32_e32 v179, v179, v236, vcc
	v_cndmask_b32_e32 v180, v237, v180, vcc
	v_cndmask_b32_e32 v181, v240, v181, vcc
	v_cndmask_b32_e32 v182, v241, v182, vcc
	v_cndmask_b32_e32 v183, v242, v183, vcc
	v_pk_add_f32 v[116:117], v[116:117], v[170:171]
	v_pk_add_f32 v[114:115], v[114:115], v[168:169]
	v_pk_add_f32 v[108:109], v[108:109], v[174:175]
	v_pk_add_f32 v[106:107], v[106:107], v[172:173]
	v_pk_add_f32 v[104:105], v[104:105], v[178:179]
	v_pk_add_f32 v[102:103], v[102:103], v[176:177]
	v_pk_add_f32 v[96:97], v[96:97], v[182:183]
	v_pk_add_f32 v[94:95], v[94:95], v[180:181]
	v_cvt_pk_bf16_f32 v114, v114, v115
	v_cvt_pk_bf16_f32 v115, v116, v117
	v_cvt_pk_bf16_f32 v106, v106, v107
	v_cvt_pk_bf16_f32 v107, v108, v109
	v_cvt_pk_bf16_f32 v102, v102, v103
	v_cvt_pk_bf16_f32 v103, v104, v105
	v_cvt_pk_bf16_f32 v94, v94, v95
	v_cvt_pk_bf16_f32 v95, v96, v97
	ds_bpermute_b32 v168, v244, v114
	ds_bpermute_b32 v169, v244, v115
	ds_bpermute_b32 v170, v244, v106
	ds_bpermute_b32 v171, v244, v107
	ds_bpermute_b32 v172, v245, v114
	ds_bpermute_b32 v173, v245, v115
	ds_bpermute_b32 v174, v245, v106
	ds_bpermute_b32 v175, v245, v107
	s_waitcnt lgkmcnt(0)
	v_cndmask_b32_e64 v168, v168, v170, s[98:99]
	v_cndmask_b32_e64 v169, v169, v171, s[98:99]
	v_add_u32_e32 v170, 0x8000, v246
	global_store_dwordx2 v170, v[168:169], s[48:49]
	v_cndmask_b32_e64 v172, v172, v174, s[98:99]
	v_cndmask_b32_e64 v173, v173, v175, s[98:99]
	v_add_u32_e32 v174, 0xc000, v246
	global_store_dwordx2 v174, v[172:173], s[48:49]
	ds_bpermute_b32 v168, v244, v102
	ds_bpermute_b32 v169, v244, v103
	ds_bpermute_b32 v170, v244, v94
	ds_bpermute_b32 v171, v244, v95
	ds_bpermute_b32 v172, v245, v102
	ds_bpermute_b32 v173, v245, v103
	ds_bpermute_b32 v174, v245, v94
	ds_bpermute_b32 v175, v245, v95
	s_waitcnt lgkmcnt(0)
	v_cndmask_b32_e64 v168, v168, v170, s[98:99]
	v_cndmask_b32_e64 v169, v169, v171, s[98:99]
	v_add_u32_e32 v170, 0x8000, v246
	global_store_dwordx2 v170, v[168:169], s[48:49] offset:256
	v_cndmask_b32_e64 v172, v172, v174, s[98:99]
	v_cndmask_b32_e64 v173, v173, v175, s[98:99]
	v_add_u32_e32 v174, 0xc000, v246
	global_store_dwordx2 v174, v[172:173], s[48:49] offset:256
	v_add_u32_e32 v251, 0x90000, v255
	global_load_dwordx4 v[168:171], v251, s[60:61]
	global_load_dwordx4 v[176:179], v251, s[60:61] offset:512
	v_add_u32_e32 v252, 0x98000, v255
	global_load_dwordx4 v[172:175], v252, s[60:61]
	global_load_dwordx4 v[180:183], v252, s[60:61] offset:512
	s_waitcnt vmcnt(20)
	ds_bpermute_b32 v229, v254, v184
	ds_bpermute_b32 v230, v254, v185
	ds_bpermute_b32 v231, v254, v186
	ds_bpermute_b32 v232, v254, v187
	ds_bpermute_b32 v225, v253, v188
	ds_bpermute_b32 v226, v253, v189
	ds_bpermute_b32 v227, v253, v190
	ds_bpermute_b32 v228, v253, v191
	ds_bpermute_b32 v184, v253, v184
	ds_bpermute_b32 v185, v253, v185
	ds_bpermute_b32 v186, v253, v186
	ds_bpermute_b32 v187, v253, v187
	ds_bpermute_b32 v188, v254, v188
	ds_bpermute_b32 v189, v254, v189
	ds_bpermute_b32 v190, v254, v190
	ds_bpermute_b32 v191, v254, v191
	s_waitcnt lgkmcnt(0)
	v_cndmask_b32_e32 v184, v184, v225, vcc
	v_cndmask_b32_e32 v185, v185, v226, vcc
	v_cndmask_b32_e32 v186, v186, v227, vcc
	v_cndmask_b32_e32 v187, v187, v228, vcc
	v_cndmask_b32_e32 v188, v229, v188, vcc
	v_cndmask_b32_e32 v189, v230, v189, vcc
	v_cndmask_b32_e32 v190, v231, v190, vcc
	v_cndmask_b32_e32 v191, v232, v191, vcc
	ds_bpermute_b32 v237, v254, v192
	ds_bpermute_b32 v240, v254, v193
	ds_bpermute_b32 v241, v254, v194
	ds_bpermute_b32 v242, v254, v195
	ds_bpermute_b32 v233, v253, v198
	ds_bpermute_b32 v234, v253, v199
	ds_bpermute_b32 v235, v253, v200
	ds_bpermute_b32 v236, v253, v201
	ds_bpermute_b32 v192, v253, v192
	ds_bpermute_b32 v193, v253, v193
	ds_bpermute_b32 v194, v253, v194
	ds_bpermute_b32 v195, v253, v195
	ds_bpermute_b32 v198, v254, v198
	ds_bpermute_b32 v199, v254, v199
	ds_bpermute_b32 v200, v254, v200
	ds_bpermute_b32 v201, v254, v201
	s_waitcnt lgkmcnt(0)
	v_cndmask_b32_e32 v192, v192, v233, vcc
	v_cndmask_b32_e32 v193, v193, v234, vcc
	v_cndmask_b32_e32 v194, v194, v235, vcc
	v_cndmask_b32_e32 v195, v195, v236, vcc
	v_cndmask_b32_e32 v198, v237, v198, vcc
	v_cndmask_b32_e32 v199, v240, v199, vcc
	v_cndmask_b32_e32 v200, v241, v200, vcc
	v_cndmask_b32_e32 v201, v242, v201, vcc
	v_pk_add_f32 v[100:101], v[100:101], v[186:187]
	v_pk_add_f32 v[98:99], v[98:99], v[184:185]
	v_pk_add_f32 v[92:93], v[92:93], v[190:191]
	v_pk_add_f32 v[90:91], v[90:91], v[188:189]
	v_pk_add_f32 v[88:89], v[88:89], v[194:195]
	v_pk_add_f32 v[86:87], v[86:87], v[192:193]
	v_pk_add_f32 v[80:81], v[80:81], v[200:201]
	v_pk_add_f32 v[78:79], v[78:79], v[198:199]
	v_cvt_pk_bf16_f32 v98, v98, v99
	v_cvt_pk_bf16_f32 v99, v100, v101
	v_cvt_pk_bf16_f32 v90, v90, v91
	v_cvt_pk_bf16_f32 v91, v92, v93
	v_cvt_pk_bf16_f32 v86, v86, v87
	v_cvt_pk_bf16_f32 v87, v88, v89
	v_cvt_pk_bf16_f32 v78, v78, v79
	v_cvt_pk_bf16_f32 v79, v80, v81
	ds_bpermute_b32 v184, v244, v98
	ds_bpermute_b32 v185, v244, v99
	ds_bpermute_b32 v186, v244, v90
	ds_bpermute_b32 v187, v244, v91
	ds_bpermute_b32 v188, v245, v98
	ds_bpermute_b32 v189, v245, v99
	ds_bpermute_b32 v190, v245, v90
	ds_bpermute_b32 v191, v245, v91
	s_waitcnt lgkmcnt(0)
	v_cndmask_b32_e64 v184, v184, v186, s[98:99]
	v_cndmask_b32_e64 v185, v185, v187, s[98:99]
	v_add_u32_e32 v186, 0x10000, v246
	global_store_dwordx2 v186, v[184:185], s[48:49]
	v_cndmask_b32_e64 v188, v188, v190, s[98:99]
	v_cndmask_b32_e64 v189, v189, v191, s[98:99]
	v_add_u32_e32 v190, 0x14000, v246
	global_store_dwordx2 v190, v[188:189], s[48:49]
	ds_bpermute_b32 v184, v244, v86
	ds_bpermute_b32 v185, v244, v87
	ds_bpermute_b32 v186, v244, v78
	ds_bpermute_b32 v187, v244, v79
	ds_bpermute_b32 v188, v245, v86
	ds_bpermute_b32 v189, v245, v87
	ds_bpermute_b32 v190, v245, v78
	ds_bpermute_b32 v191, v245, v79
	s_waitcnt lgkmcnt(0)
; DI unsigned pk_bf16(float a, float b) { f32x2 v = {a, b}; bf2_t r = __builtin_convertvector(v, bf2_t); return __builtin_bit_cast(unsigned, r); }
; DI float bflo(unsigned u) { return __uint_as_float(u << 16); }
; DI float bfhi(unsigned u) { return __uint_as_float(u & 0xffff0000u); }
;     DI void operator()(const f32x4 (&acc)[2][2][4][2], const Unit& u, int wr, int wc, int fr, int fq) const {
;         const int row0 = u.pm * BM + wr * 64 + fr, col0 = u.pn * BM + wc * 32 + 4 * fq;
; #pragma unroll
;         for (int ai = 0; ai < 2; ++ai)
; #pragma unroll
;             for (int m = 0; m < 4; ++m) { const size_t o = (size_t)(row0 + ai * HALF + m * 16) * 1024 + col0;
; #pragma unroll
;                 for (int bj = 0; bj < 2; ++bj)
; #pragma unroll
;                     for (int n = 0; n < 2; ++n) { const size_t oo = o + bj * HALF + n * 16; f32x4 rv;
;                         if (RES_BF16) { const u32x2 t = *(const u32x2*)((const bf16_t*)res + oo); rv = (f32x4){bflo(t.x), bfhi(t.x), bflo(t.y), bfhi(t.y)}; }
;                         else rv = *(const f32x4*)((const float*)res + oo);
;                         const f32x4 v = acc[ai][bj][m][n] + rv; u32x2 w; w.x = pk_bf16(v.x, v.y); w.y = pk_bf16(v.z, v.w);
;                         *(u32x2*)(O + oo) = w; } }
	v_cndmask_b32_e64 v184, v184, v186, s[98:99]
	v_cndmask_b32_e64 v185, v185, v187, s[98:99]
	v_add_u32_e32 v186, 0x10000, v246
	global_store_dwordx2 v186, v[184:185], s[48:49] offset:256
	v_cndmask_b32_e64 v188, v188, v190, s[98:99]
	v_cndmask_b32_e64 v189, v189, v191, s[98:99]
	v_add_u32_e32 v190, 0x14000, v246
	global_store_dwordx2 v190, v[188:189], s[48:49] offset:256
	v_add_u32_e32 v251, 0xa0000, v255
	global_load_dwordx4 v[184:187], v251, s[60:61]
	global_load_dwordx4 v[192:195], v251, s[60:61] offset:512
	v_add_u32_e32 v252, 0xa8000, v255
	global_load_dwordx4 v[188:191], v252, s[60:61]
	global_load_dwordx4 v[198:201], v252, s[60:61] offset:512
	s_waitcnt vmcnt(24)
	ds_bpermute_b32 v229, v254, v202
	ds_bpermute_b32 v230, v254, v203
	ds_bpermute_b32 v231, v254, v204
	ds_bpermute_b32 v232, v254, v205
	ds_bpermute_b32 v225, v253, v206
	ds_bpermute_b32 v226, v253, v207
	ds_bpermute_b32 v227, v253, v208
	ds_bpermute_b32 v228, v253, v209
	ds_bpermute_b32 v202, v253, v202
	ds_bpermute_b32 v203, v253, v203
	ds_bpermute_b32 v204, v253, v204
	ds_bpermute_b32 v205, v253, v205
	ds_bpermute_b32 v206, v254, v206
	ds_bpermute_b32 v207, v254, v207
	ds_bpermute_b32 v208, v254, v208
	ds_bpermute_b32 v209, v254, v209
	s_waitcnt lgkmcnt(0)
	v_cndmask_b32_e32 v202, v202, v225, vcc
	v_cndmask_b32_e32 v203, v203, v226, vcc
	v_cndmask_b32_e32 v204, v204, v227, vcc
	v_cndmask_b32_e32 v205, v205, v228, vcc
	v_cndmask_b32_e32 v206, v229, v206, vcc
	v_cndmask_b32_e32 v207, v230, v207, vcc
	v_cndmask_b32_e32 v208, v231, v208, vcc
	v_cndmask_b32_e32 v209, v232, v209, vcc
	ds_bpermute_b32 v237, v254, v210
	ds_bpermute_b32 v240, v254, v211
	ds_bpermute_b32 v241, v254, v212
	ds_bpermute_b32 v242, v254, v213
	ds_bpermute_b32 v233, v253, v214
	ds_bpermute_b32 v234, v253, v215
	ds_bpermute_b32 v235, v253, v216
	ds_bpermute_b32 v236, v253, v217
	ds_bpermute_b32 v210, v253, v210
	ds_bpermute_b32 v211, v253, v211
	ds_bpermute_b32 v212, v253, v212
	ds_bpermute_b32 v213, v253, v213
	ds_bpermute_b32 v214, v254, v214
	ds_bpermute_b32 v215, v254, v215
	ds_bpermute_b32 v216, v254, v216
	ds_bpermute_b32 v217, v254, v217
	s_waitcnt lgkmcnt(0)
	v_cndmask_b32_e32 v210, v210, v233, vcc
	v_cndmask_b32_e32 v211, v211, v234, vcc
	v_cndmask_b32_e32 v212, v212, v235, vcc
	v_cndmask_b32_e32 v213, v213, v236, vcc
	v_cndmask_b32_e32 v214, v237, v214, vcc
	v_cndmask_b32_e32 v215, v240, v215, vcc
	v_cndmask_b32_e32 v216, v241, v216, vcc
	v_cndmask_b32_e32 v217, v242, v217, vcc
	v_pk_add_f32 v[84:85], v[84:85], v[204:205]
	v_pk_add_f32 v[82:83], v[82:83], v[202:203]
	v_pk_add_f32 v[76:77], v[76:77], v[208:209]
	v_pk_add_f32 v[74:75], v[74:75], v[206:207]
	v_pk_add_f32 v[72:73], v[72:73], v[212:213]
	v_pk_add_f32 v[70:71], v[70:71], v[210:211]
	v_pk_add_f32 v[68:69], v[68:69], v[216:217]
	v_pk_add_f32 v[66:67], v[66:67], v[214:215]
	v_cvt_pk_bf16_f32 v82, v82, v83
	v_cvt_pk_bf16_f32 v83, v84, v85
	v_cvt_pk_bf16_f32 v74, v74, v75
	v_cvt_pk_bf16_f32 v75, v76, v77
	v_cvt_pk_bf16_f32 v70, v70, v71
	v_cvt_pk_bf16_f32 v71, v72, v73
	v_cvt_pk_bf16_f32 v66, v66, v67
	v_cvt_pk_bf16_f32 v67, v68, v69
	ds_bpermute_b32 v202, v244, v82
	ds_bpermute_b32 v203, v244, v83
	ds_bpermute_b32 v204, v244, v74
	ds_bpermute_b32 v205, v244, v75
	ds_bpermute_b32 v206, v245, v82
	ds_bpermute_b32 v207, v245, v83
	ds_bpermute_b32 v208, v245, v74
	ds_bpermute_b32 v209, v245, v75
	s_waitcnt lgkmcnt(0)
	v_cndmask_b32_e64 v202, v202, v204, s[98:99]
	v_cndmask_b32_e64 v203, v203, v205, s[98:99]
	v_add_u32_e32 v204, 0x18000, v246
	global_store_dwordx2 v204, v[202:203], s[48:49]
	v_cndmask_b32_e64 v206, v206, v208, s[98:99]
	v_cndmask_b32_e64 v207, v207, v209, s[98:99]
	v_add_u32_e32 v208, 0x1c000, v246
	global_store_dwordx2 v208, v[206:207], s[48:49]
	ds_bpermute_b32 v202, v244, v70
	ds_bpermute_b32 v203, v244, v71
	ds_bpermute_b32 v204, v244, v66
	ds_bpermute_b32 v205, v244, v67
	ds_bpermute_b32 v206, v245, v70
	ds_bpermute_b32 v207, v245, v71
	ds_bpermute_b32 v208, v245, v66
	ds_bpermute_b32 v209, v245, v67
	s_waitcnt lgkmcnt(0)
	v_cndmask_b32_e64 v202, v202, v204, s[98:99]
	v_cndmask_b32_e64 v203, v203, v205, s[98:99]
	v_add_u32_e32 v204, 0x18000, v246
	global_store_dwordx2 v204, v[202:203], s[48:49] offset:256
	v_cndmask_b32_e64 v206, v206, v208, s[98:99]
	v_cndmask_b32_e64 v207, v207, v209, s[98:99]
	v_add_u32_e32 v208, 0x1c000, v246
	global_store_dwordx2 v208, v[206:207], s[48:49] offset:256
	v_add_u32_e32 v251, 0xb0000, v255
	global_load_dwordx4 v[202:205], v251, s[60:61]
	global_load_dwordx4 v[210:213], v251, s[60:61] offset:512
	v_add_u32_e32 v252, 0xb8000, v255
	global_load_dwordx4 v[206:209], v252, s[60:61]
	global_load_dwordx4 v[214:217], v252, s[60:61] offset:512
	s_waitcnt vmcnt(24)
	ds_bpermute_b32 v229, v254, v140
	ds_bpermute_b32 v230, v254, v141
	ds_bpermute_b32 v231, v254, v142
	ds_bpermute_b32 v232, v254, v143
	ds_bpermute_b32 v225, v253, v154
	ds_bpermute_b32 v226, v253, v155
	ds_bpermute_b32 v227, v253, v156
	ds_bpermute_b32 v228, v253, v157
	ds_bpermute_b32 v140, v253, v140
	ds_bpermute_b32 v141, v253, v141
	ds_bpermute_b32 v142, v253, v142
	ds_bpermute_b32 v143, v253, v143
	ds_bpermute_b32 v154, v254, v154
	ds_bpermute_b32 v155, v254, v155
	ds_bpermute_b32 v156, v254, v156
	ds_bpermute_b32 v157, v254, v157
	s_waitcnt lgkmcnt(0)
; DI unsigned pk_bf16(float a, float b) { f32x2 v = {a, b}; bf2_t r = __builtin_convertvector(v, bf2_t); return __builtin_bit_cast(unsigned, r); }
; DI float bflo(unsigned u) { return __uint_as_float(u << 16); }
; DI float bfhi(unsigned u) { return __uint_as_float(u & 0xffff0000u); }
;     DI void operator()(const f32x4 (&acc)[2][2][4][2], const Unit& u, int wr, int wc, int fr, int fq) const {
;         const int row0 = u.pm * BM + wr * 64 + fr, col0 = u.pn * BM + wc * 32 + 4 * fq;
; #pragma unroll
;         for (int ai = 0; ai < 2; ++ai)
; #pragma unroll
;             for (int m = 0; m < 4; ++m) { const size_t o = (size_t)(row0 + ai * HALF + m * 16) * 1024 + col0;
; #pragma unroll
;                 for (int bj = 0; bj < 2; ++bj)
; #pragma unroll
;                     for (int n = 0; n < 2; ++n) { const size_t oo = o + bj * HALF + n * 16; f32x4 rv;
;                         if (RES_BF16) { const u32x2 t = *(const u32x2*)((const bf16_t*)res + oo); rv = (f32x4){bflo(t.x), bfhi(t.x), bflo(t.y), bfhi(t.y)}; }
;                         else rv = *(const f32x4*)((const float*)res + oo);
;                         const f32x4 v = acc[ai][bj][m][n] + rv; u32x2 w; w.x = pk_bf16(v.x, v.y); w.y = pk_bf16(v.z, v.w);
;                         *(u32x2*)(O + oo) = w; } }
	v_cndmask_b32_e32 v140, v140, v225, vcc
	v_cndmask_b32_e32 v141, v141, v226, vcc
	v_cndmask_b32_e32 v142, v142, v227, vcc
	v_cndmask_b32_e32 v143, v143, v228, vcc
	v_cndmask_b32_e32 v154, v229, v154, vcc
	v_cndmask_b32_e32 v155, v230, v155, vcc
	v_cndmask_b32_e32 v156, v231, v156, vcc
	v_cndmask_b32_e32 v157, v232, v157, vcc
	ds_bpermute_b32 v237, v254, v158
	ds_bpermute_b32 v240, v254, v159
	ds_bpermute_b32 v241, v254, v160
	ds_bpermute_b32 v242, v254, v161
	ds_bpermute_b32 v233, v253, v164
	ds_bpermute_b32 v234, v253, v165
	ds_bpermute_b32 v235, v253, v166
	ds_bpermute_b32 v236, v253, v167
	ds_bpermute_b32 v158, v253, v158
	ds_bpermute_b32 v159, v253, v159
	ds_bpermute_b32 v160, v253, v160
	ds_bpermute_b32 v161, v253, v161
	ds_bpermute_b32 v164, v254, v164
	ds_bpermute_b32 v165, v254, v165
	ds_bpermute_b32 v166, v254, v166
	ds_bpermute_b32 v167, v254, v167
	s_waitcnt lgkmcnt(0)
	v_cndmask_b32_e32 v158, v158, v233, vcc
	v_cndmask_b32_e32 v159, v159, v234, vcc
	v_cndmask_b32_e32 v160, v160, v235, vcc
	v_cndmask_b32_e32 v161, v161, v236, vcc
	v_cndmask_b32_e32 v164, v237, v164, vcc
	v_cndmask_b32_e32 v165, v240, v165, vcc
	v_cndmask_b32_e32 v166, v241, v166, vcc
	v_cndmask_b32_e32 v167, v242, v167, vcc
	v_pk_add_f32 v[64:65], v[64:65], v[142:143]
	v_pk_add_f32 v[62:63], v[62:63], v[140:141]
	v_pk_add_f32 v[60:61], v[60:61], v[156:157]
	v_pk_add_f32 v[58:59], v[58:59], v[154:155]
	v_pk_add_f32 v[56:57], v[56:57], v[160:161]
	v_pk_add_f32 v[54:55], v[54:55], v[158:159]
	v_pk_add_f32 v[48:49], v[48:49], v[166:167]
	v_pk_add_f32 v[46:47], v[46:47], v[164:165]
	v_cvt_pk_bf16_f32 v62, v62, v63
	v_cvt_pk_bf16_f32 v63, v64, v65
	v_cvt_pk_bf16_f32 v58, v58, v59
	v_cvt_pk_bf16_f32 v59, v60, v61
	v_cvt_pk_bf16_f32 v54, v54, v55
	v_cvt_pk_bf16_f32 v55, v56, v57
	v_cvt_pk_bf16_f32 v46, v46, v47
	v_cvt_pk_bf16_f32 v47, v48, v49
	ds_bpermute_b32 v140, v244, v62
	ds_bpermute_b32 v141, v244, v63
	ds_bpermute_b32 v142, v244, v58
	ds_bpermute_b32 v143, v244, v59
	ds_bpermute_b32 v154, v245, v62
	ds_bpermute_b32 v155, v245, v63
	ds_bpermute_b32 v156, v245, v58
	ds_bpermute_b32 v157, v245, v59
	s_waitcnt lgkmcnt(0)
	v_cndmask_b32_e64 v140, v140, v142, s[98:99]
	v_cndmask_b32_e64 v141, v141, v143, s[98:99]
	v_add_u32_e32 v142, 0x40000, v246
	global_store_dwordx2 v142, v[140:141], s[48:49]
	v_cndmask_b32_e64 v154, v154, v156, s[98:99]
	v_cndmask_b32_e64 v155, v155, v157, s[98:99]
	v_add_u32_e32 v156, 0x44000, v246
	global_store_dwordx2 v156, v[154:155], s[48:49]
	ds_bpermute_b32 v140, v244, v54
	ds_bpermute_b32 v141, v244, v55
	ds_bpermute_b32 v142, v244, v46
	ds_bpermute_b32 v143, v244, v47
	ds_bpermute_b32 v154, v245, v54
	ds_bpermute_b32 v155, v245, v55
	ds_bpermute_b32 v156, v245, v46
	ds_bpermute_b32 v157, v245, v47
	s_waitcnt lgkmcnt(0)
	v_cndmask_b32_e64 v140, v140, v142, s[98:99]
	v_cndmask_b32_e64 v141, v141, v143, s[98:99]
	v_add_u32_e32 v142, 0x40000, v246
	global_store_dwordx2 v142, v[140:141], s[48:49] offset:256
	v_cndmask_b32_e64 v154, v154, v156, s[98:99]
	v_cndmask_b32_e64 v155, v155, v157, s[98:99]
	v_add_u32_e32 v156, 0x44000, v246
	global_store_dwordx2 v156, v[154:155], s[48:49] offset:256
	s_waitcnt vmcnt(20)
	ds_bpermute_b32 v229, v254, v168
	ds_bpermute_b32 v230, v254, v169
	ds_bpermute_b32 v231, v254, v170
	ds_bpermute_b32 v232, v254, v171
	ds_bpermute_b32 v225, v253, v172
	ds_bpermute_b32 v226, v253, v173
	ds_bpermute_b32 v227, v253, v174
	ds_bpermute_b32 v228, v253, v175
	ds_bpermute_b32 v168, v253, v168
	ds_bpermute_b32 v169, v253, v169
	ds_bpermute_b32 v170, v253, v170
	ds_bpermute_b32 v171, v253, v171
	ds_bpermute_b32 v172, v254, v172
	ds_bpermute_b32 v173, v254, v173
	ds_bpermute_b32 v174, v254, v174
	ds_bpermute_b32 v175, v254, v175
	s_waitcnt lgkmcnt(0)
	v_cndmask_b32_e32 v168, v168, v225, vcc
	v_cndmask_b32_e32 v169, v169, v226, vcc
	v_cndmask_b32_e32 v170, v170, v227, vcc
	v_cndmask_b32_e32 v171, v171, v228, vcc
	v_cndmask_b32_e32 v172, v229, v172, vcc
	v_cndmask_b32_e32 v173, v230, v173, vcc
	v_cndmask_b32_e32 v174, v231, v174, vcc
	v_cndmask_b32_e32 v175, v232, v175, vcc
	ds_bpermute_b32 v237, v254, v176
	ds_bpermute_b32 v240, v254, v177
	ds_bpermute_b32 v241, v254, v178
	ds_bpermute_b32 v242, v254, v179
	ds_bpermute_b32 v233, v253, v180
	ds_bpermute_b32 v234, v253, v181
	ds_bpermute_b32 v235, v253, v182
	ds_bpermute_b32 v236, v253, v183
	ds_bpermute_b32 v176, v253, v176
	ds_bpermute_b32 v177, v253, v177
	ds_bpermute_b32 v178, v253, v178
	ds_bpermute_b32 v179, v253, v179
	ds_bpermute_b32 v180, v254, v180
	ds_bpermute_b32 v181, v254, v181
	ds_bpermute_b32 v182, v254, v182
	ds_bpermute_b32 v183, v254, v183
	s_waitcnt lgkmcnt(0)
	v_cndmask_b32_e32 v176, v176, v233, vcc
	v_cndmask_b32_e32 v177, v177, v234, vcc
	v_cndmask_b32_e32 v178, v178, v235, vcc
	v_cndmask_b32_e32 v179, v179, v236, vcc
	v_cndmask_b32_e32 v180, v237, v180, vcc
	v_cndmask_b32_e32 v181, v240, v181, vcc
	v_cndmask_b32_e32 v182, v241, v182, vcc
	v_cndmask_b32_e32 v183, v242, v183, vcc
	v_pk_add_f32 v[52:53], v[52:53], v[170:171]
	v_pk_add_f32 v[50:51], v[50:51], v[168:169]
	v_pk_add_f32 v[44:45], v[44:45], v[174:175]
	v_pk_add_f32 v[42:43], v[42:43], v[172:173]
	v_pk_add_f32 v[40:41], v[40:41], v[178:179]
	v_pk_add_f32 v[38:39], v[38:39], v[176:177]
	v_pk_add_f32 v[32:33], v[32:33], v[182:183]
	v_pk_add_f32 v[30:31], v[30:31], v[180:181]
	v_cvt_pk_bf16_f32 v50, v50, v51
	v_cvt_pk_bf16_f32 v51, v52, v53
	v_cvt_pk_bf16_f32 v42, v42, v43
	v_cvt_pk_bf16_f32 v43, v44, v45
	v_cvt_pk_bf16_f32 v38, v38, v39
	v_cvt_pk_bf16_f32 v39, v40, v41
	v_cvt_pk_bf16_f32 v30, v30, v31
	v_cvt_pk_bf16_f32 v31, v32, v33
	ds_bpermute_b32 v168, v244, v50
	ds_bpermute_b32 v169, v244, v51
	ds_bpermute_b32 v170, v244, v42
	ds_bpermute_b32 v171, v244, v43
	ds_bpermute_b32 v172, v245, v50
	ds_bpermute_b32 v173, v245, v51
	ds_bpermute_b32 v174, v245, v42
	ds_bpermute_b32 v175, v245, v43
	s_waitcnt lgkmcnt(0)
; DI unsigned pk_bf16(float a, float b) { f32x2 v = {a, b}; bf2_t r = __builtin_convertvector(v, bf2_t); return __builtin_bit_cast(unsigned, r); }
; DI float bflo(unsigned u) { return __uint_as_float(u << 16); }
; DI float bfhi(unsigned u) { return __uint_as_float(u & 0xffff0000u); }
;     DI void operator()(const f32x4 (&acc)[2][2][4][2], const Unit& u, int wr, int wc, int fr, int fq) const {
;         const int row0 = u.pm * BM + wr * 64 + fr, col0 = u.pn * BM + wc * 32 + 4 * fq;
; #pragma unroll
;         for (int ai = 0; ai < 2; ++ai)
; #pragma unroll
;             for (int m = 0; m < 4; ++m) { const size_t o = (size_t)(row0 + ai * HALF + m * 16) * 1024 + col0;
; #pragma unroll
;                 for (int bj = 0; bj < 2; ++bj)
; #pragma unroll
;                     for (int n = 0; n < 2; ++n) { const size_t oo = o + bj * HALF + n * 16; f32x4 rv;
;                         if (RES_BF16) { const u32x2 t = *(const u32x2*)((const bf16_t*)res + oo); rv = (f32x4){bflo(t.x), bfhi(t.x), bflo(t.y), bfhi(t.y)}; }
;                         else rv = *(const f32x4*)((const float*)res + oo);
;                         const f32x4 v = acc[ai][bj][m][n] + rv; u32x2 w; w.x = pk_bf16(v.x, v.y); w.y = pk_bf16(v.z, v.w);
;                         *(u32x2*)(O + oo) = w; } }
	v_cndmask_b32_e64 v168, v168, v170, s[98:99]
	v_cndmask_b32_e64 v169, v169, v171, s[98:99]
	v_add_u32_e32 v170, 0x48000, v246
	global_store_dwordx2 v170, v[168:169], s[48:49]
	v_cndmask_b32_e64 v172, v172, v174, s[98:99]
	v_cndmask_b32_e64 v173, v173, v175, s[98:99]
	v_add_u32_e32 v174, 0x4c000, v246
	global_store_dwordx2 v174, v[172:173], s[48:49]
	ds_bpermute_b32 v168, v244, v38
	ds_bpermute_b32 v169, v244, v39
	ds_bpermute_b32 v170, v244, v30
	ds_bpermute_b32 v171, v244, v31
	ds_bpermute_b32 v172, v245, v38
	ds_bpermute_b32 v173, v245, v39
	ds_bpermute_b32 v174, v245, v30
	ds_bpermute_b32 v175, v245, v31
	s_waitcnt lgkmcnt(0)
	v_cndmask_b32_e64 v168, v168, v170, s[98:99]
	v_cndmask_b32_e64 v169, v169, v171, s[98:99]
	v_add_u32_e32 v170, 0x48000, v246
	global_store_dwordx2 v170, v[168:169], s[48:49] offset:256
	v_cndmask_b32_e64 v172, v172, v174, s[98:99]
	v_cndmask_b32_e64 v173, v173, v175, s[98:99]
	v_add_u32_e32 v174, 0x4c000, v246
	global_store_dwordx2 v174, v[172:173], s[48:49] offset:256
	s_waitcnt vmcnt(16)
	ds_bpermute_b32 v229, v254, v184
	ds_bpermute_b32 v230, v254, v185
	ds_bpermute_b32 v231, v254, v186
	ds_bpermute_b32 v232, v254, v187
	ds_bpermute_b32 v225, v253, v188
	ds_bpermute_b32 v226, v253, v189
	ds_bpermute_b32 v227, v253, v190
	ds_bpermute_b32 v228, v253, v191
	ds_bpermute_b32 v184, v253, v184
	ds_bpermute_b32 v185, v253, v185
	ds_bpermute_b32 v186, v253, v186
	ds_bpermute_b32 v187, v253, v187
	ds_bpermute_b32 v188, v254, v188
	ds_bpermute_b32 v189, v254, v189
	ds_bpermute_b32 v190, v254, v190
	ds_bpermute_b32 v191, v254, v191
	s_waitcnt lgkmcnt(0)
	v_cndmask_b32_e32 v184, v184, v225, vcc
	v_cndmask_b32_e32 v185, v185, v226, vcc
	v_cndmask_b32_e32 v186, v186, v227, vcc
	v_cndmask_b32_e32 v187, v187, v228, vcc
	v_cndmask_b32_e32 v188, v229, v188, vcc
	v_cndmask_b32_e32 v189, v230, v189, vcc
	v_cndmask_b32_e32 v190, v231, v190, vcc
	v_cndmask_b32_e32 v191, v232, v191, vcc
	ds_bpermute_b32 v237, v254, v192
	ds_bpermute_b32 v240, v254, v193
	ds_bpermute_b32 v241, v254, v194
	ds_bpermute_b32 v242, v254, v195
	ds_bpermute_b32 v233, v253, v198
	ds_bpermute_b32 v234, v253, v199
	ds_bpermute_b32 v235, v253, v200
	ds_bpermute_b32 v236, v253, v201
	ds_bpermute_b32 v192, v253, v192
	ds_bpermute_b32 v193, v253, v193
	ds_bpermute_b32 v194, v253, v194
	ds_bpermute_b32 v195, v253, v195
	ds_bpermute_b32 v198, v254, v198
	ds_bpermute_b32 v199, v254, v199
	ds_bpermute_b32 v200, v254, v200
	ds_bpermute_b32 v201, v254, v201
	s_waitcnt lgkmcnt(0)
	v_cndmask_b32_e32 v192, v192, v233, vcc
	v_cndmask_b32_e32 v193, v193, v234, vcc
	v_cndmask_b32_e32 v194, v194, v235, vcc
	v_cndmask_b32_e32 v195, v195, v236, vcc
	v_cndmask_b32_e32 v198, v237, v198, vcc
	v_cndmask_b32_e32 v199, v240, v199, vcc
	v_cndmask_b32_e32 v200, v241, v200, vcc
	v_cndmask_b32_e32 v201, v242, v201, vcc
	v_pk_add_f32 v[36:37], v[36:37], v[186:187]
	v_pk_add_f32 v[34:35], v[34:35], v[184:185]
	v_pk_add_f32 v[28:29], v[28:29], v[190:191]
	v_pk_add_f32 v[26:27], v[26:27], v[188:189]
	v_pk_add_f32 v[24:25], v[24:25], v[194:195]
	v_pk_add_f32 v[22:23], v[22:23], v[192:193]
	v_pk_add_f32 v[16:17], v[16:17], v[200:201]
	v_pk_add_f32 v[14:15], v[14:15], v[198:199]
	v_cvt_pk_bf16_f32 v34, v34, v35
	v_cvt_pk_bf16_f32 v35, v36, v37
	v_cvt_pk_bf16_f32 v26, v26, v27
	v_cvt_pk_bf16_f32 v27, v28, v29
	v_cvt_pk_bf16_f32 v22, v22, v23
	v_cvt_pk_bf16_f32 v23, v24, v25
	v_cvt_pk_bf16_f32 v14, v14, v15
	v_cvt_pk_bf16_f32 v15, v16, v17
	ds_bpermute_b32 v184, v244, v34
	ds_bpermute_b32 v185, v244, v35
	ds_bpermute_b32 v186, v244, v26
	ds_bpermute_b32 v187, v244, v27
	ds_bpermute_b32 v188, v245, v34
	ds_bpermute_b32 v189, v245, v35
	ds_bpermute_b32 v190, v245, v26
	ds_bpermute_b32 v191, v245, v27
	s_waitcnt lgkmcnt(0)
	v_cndmask_b32_e64 v184, v184, v186, s[98:99]
	v_cndmask_b32_e64 v185, v185, v187, s[98:99]
	v_add_u32_e32 v186, 0x50000, v246
	global_store_dwordx2 v186, v[184:185], s[48:49]
	v_cndmask_b32_e64 v188, v188, v190, s[98:99]
	v_cndmask_b32_e64 v189, v189, v191, s[98:99]
	v_add_u32_e32 v190, 0x54000, v246
	global_store_dwordx2 v190, v[188:189], s[48:49]
	ds_bpermute_b32 v184, v244, v22
	ds_bpermute_b32 v185, v244, v23
	ds_bpermute_b32 v186, v244, v14
	ds_bpermute_b32 v187, v244, v15
	ds_bpermute_b32 v188, v245, v22
	ds_bpermute_b32 v189, v245, v23
	ds_bpermute_b32 v190, v245, v14
	ds_bpermute_b32 v191, v245, v15
	s_waitcnt lgkmcnt(0)
; DI unsigned pk_bf16(float a, float b) { f32x2 v = {a, b}; bf2_t r = __builtin_convertvector(v, bf2_t); return __builtin_bit_cast(unsigned, r); }
; DI float bflo(unsigned u) { return __uint_as_float(u << 16); }
; DI float bfhi(unsigned u) { return __uint_as_float(u & 0xffff0000u); }
;     DI void operator()(const f32x4 (&acc)[2][2][4][2], const Unit& u, int wr, int wc, int fr, int fq) const {
;         const int row0 = u.pm * BM + wr * 64 + fr, col0 = u.pn * BM + wc * 32 + 4 * fq;
; #pragma unroll
;         for (int ai = 0; ai < 2; ++ai)
; #pragma unroll
;             for (int m = 0; m < 4; ++m) { const size_t o = (size_t)(row0 + ai * HALF + m * 16) * 1024 + col0;
; #pragma unroll
;                 for (int bj = 0; bj < 2; ++bj)
; #pragma unroll
;                     for (int n = 0; n < 2; ++n) { const size_t oo = o + bj * HALF + n * 16; f32x4 rv;
;                         if (RES_BF16) { const u32x2 t = *(const u32x2*)((const bf16_t*)res + oo); rv = (f32x4){bflo(t.x), bfhi(t.x), bflo(t.y), bfhi(t.y)}; }
;                         else rv = *(const f32x4*)((const float*)res + oo);
;                         const f32x4 v = acc[ai][bj][m][n] + rv; u32x2 w; w.x = pk_bf16(v.x, v.y); w.y = pk_bf16(v.z, v.w);
;                         *(u32x2*)(O + oo) = w; } }
; template <class Epi, class Sched>
; DI void gemm_phase(LAS unsigned char* lds, const Gemm g, const Sched& S, const Epi& E) {
;     ...
;         E(acc, cur, wr, wc, fr, fq);
;         if (!has_next) break;
; #pragma unroll
;         for (int a = 0; a < 2; ++a)
; #pragma unroll
;             for (int b = 0; b < 2; ++b)
; #pragma unroll
;                 for (int m = 0; m < 4; ++m)
; #pragma unroll
;                     for (int n = 0; n < 2; ++n) acc[a][b][m][n] = (f32x4){0.f, 0.f, 0.f, 0.f};
;         cur = nxt; cA = nA; cB = nB; ++ui;
	v_cndmask_b32_e64 v184, v184, v186, s[98:99]
	v_cndmask_b32_e64 v185, v185, v187, s[98:99]
	v_add_u32_e32 v186, 0x50000, v246
	global_store_dwordx2 v186, v[184:185], s[48:49] offset:256
	v_cndmask_b32_e64 v188, v188, v190, s[98:99]
	v_cndmask_b32_e64 v189, v189, v191, s[98:99]
	v_add_u32_e32 v190, 0x54000, v246
	global_store_dwordx2 v190, v[188:189], s[48:49] offset:256
	s_waitcnt vmcnt(12)
	ds_bpermute_b32 v229, v254, v202
	ds_bpermute_b32 v230, v254, v203
	ds_bpermute_b32 v231, v254, v204
	ds_bpermute_b32 v232, v254, v205
	ds_bpermute_b32 v225, v253, v206
	ds_bpermute_b32 v226, v253, v207
	ds_bpermute_b32 v227, v253, v208
	ds_bpermute_b32 v228, v253, v209
	ds_bpermute_b32 v202, v253, v202
	ds_bpermute_b32 v203, v253, v203
	ds_bpermute_b32 v204, v253, v204
	ds_bpermute_b32 v205, v253, v205
	ds_bpermute_b32 v206, v254, v206
	ds_bpermute_b32 v207, v254, v207
	ds_bpermute_b32 v208, v254, v208
	ds_bpermute_b32 v209, v254, v209
	s_waitcnt lgkmcnt(0)
	v_cndmask_b32_e32 v202, v202, v225, vcc
	v_cndmask_b32_e32 v203, v203, v226, vcc
	v_cndmask_b32_e32 v204, v204, v227, vcc
	v_cndmask_b32_e32 v205, v205, v228, vcc
	v_cndmask_b32_e32 v206, v229, v206, vcc
	v_cndmask_b32_e32 v207, v230, v207, vcc
	v_cndmask_b32_e32 v208, v231, v208, vcc
	v_cndmask_b32_e32 v209, v232, v209, vcc
	ds_bpermute_b32 v237, v254, v210
	ds_bpermute_b32 v240, v254, v211
	ds_bpermute_b32 v241, v254, v212
	ds_bpermute_b32 v242, v254, v213
	ds_bpermute_b32 v233, v253, v214
	ds_bpermute_b32 v234, v253, v215
	ds_bpermute_b32 v235, v253, v216
	ds_bpermute_b32 v236, v253, v217
	ds_bpermute_b32 v210, v253, v210
	ds_bpermute_b32 v211, v253, v211
	ds_bpermute_b32 v212, v253, v212
	ds_bpermute_b32 v213, v253, v213
	ds_bpermute_b32 v214, v254, v214
	ds_bpermute_b32 v215, v254, v215
	ds_bpermute_b32 v216, v254, v216
	ds_bpermute_b32 v217, v254, v217
	s_waitcnt lgkmcnt(0)
	v_cndmask_b32_e32 v210, v210, v233, vcc
	v_cndmask_b32_e32 v211, v211, v234, vcc
	v_cndmask_b32_e32 v212, v212, v235, vcc
	v_cndmask_b32_e32 v213, v213, v236, vcc
	v_cndmask_b32_e32 v214, v237, v214, vcc
	v_cndmask_b32_e32 v215, v240, v215, vcc
	v_cndmask_b32_e32 v216, v241, v216, vcc
	v_cndmask_b32_e32 v217, v242, v217, vcc
	v_pk_add_f32 v[20:21], v[20:21], v[204:205]
	v_pk_add_f32 v[18:19], v[18:19], v[202:203]
	v_pk_add_f32 v[12:13], v[12:13], v[208:209]
	v_pk_add_f32 v[10:11], v[10:11], v[206:207]
	v_pk_add_f32 v[8:9], v[8:9], v[212:213]
	v_pk_add_f32 v[6:7], v[6:7], v[210:211]
	v_pk_add_f32 v[4:5], v[4:5], v[216:217]
	v_pk_add_f32 v[2:3], v[2:3], v[214:215]
	v_cvt_pk_bf16_f32 v18, v18, v19
	v_cvt_pk_bf16_f32 v19, v20, v21
	v_cvt_pk_bf16_f32 v10, v10, v11
	v_cvt_pk_bf16_f32 v11, v12, v13
	v_cvt_pk_bf16_f32 v6, v6, v7
	v_cvt_pk_bf16_f32 v7, v8, v9
	v_cvt_pk_bf16_f32 v2, v2, v3
	v_cvt_pk_bf16_f32 v3, v4, v5
	ds_bpermute_b32 v202, v244, v18
	ds_bpermute_b32 v203, v244, v19
	ds_bpermute_b32 v204, v244, v10
	ds_bpermute_b32 v205, v244, v11
	ds_bpermute_b32 v206, v245, v18
	ds_bpermute_b32 v207, v245, v19
	ds_bpermute_b32 v208, v245, v10
	ds_bpermute_b32 v209, v245, v11
	s_waitcnt lgkmcnt(0)
	v_cndmask_b32_e64 v202, v202, v204, s[98:99]
	v_cndmask_b32_e64 v203, v203, v205, s[98:99]
	v_add_u32_e32 v204, 0x58000, v246
	global_store_dwordx2 v204, v[202:203], s[48:49]
	v_cndmask_b32_e64 v206, v206, v208, s[98:99]
	v_cndmask_b32_e64 v207, v207, v209, s[98:99]
	v_add_u32_e32 v208, 0x5c000, v246
	global_store_dwordx2 v208, v[206:207], s[48:49]
	ds_bpermute_b32 v202, v244, v6
	ds_bpermute_b32 v203, v244, v7
	ds_bpermute_b32 v204, v244, v2
	ds_bpermute_b32 v205, v244, v3
	ds_bpermute_b32 v206, v245, v6
	ds_bpermute_b32 v207, v245, v7
	ds_bpermute_b32 v208, v245, v2
	ds_bpermute_b32 v209, v245, v3
	s_waitcnt lgkmcnt(0)
	v_cndmask_b32_e64 v202, v202, v204, s[98:99]
	v_cndmask_b32_e64 v203, v203, v205, s[98:99]
	v_add_u32_e32 v204, 0x58000, v246
	global_store_dwordx2 v204, v[202:203], s[48:49] offset:256
	v_cndmask_b32_e64 v206, v206, v208, s[98:99]
	v_cndmask_b32_e64 v207, v207, v209, s[98:99]
	v_add_u32_e32 v208, 0x5c000, v246
	global_store_dwordx2 v208, v[206:207], s[48:49] offset:256
	s_and_b64 vcc, exec, s[20:21]
	s_mov_b32 s42, s40
	s_mov_b32 s43, s41
	s_mov_b64 s[22:23], 0x2c000
	s_cbranch_vccz .LBB0_1006
	s_waitcnt vmcnt(0)
	s_cmpk_gt_u32 s3, 0xff
	s_cbranch_scc1 .LBB0_1011
	s_barrier

; #define PG8_STAGE(bufoff, gbase, voff) do { _Pragma("unroll") for (int _i = 0; _i < 2; ++_i) \
;         __builtin_amdgcn_global_load_lds((const unsigned*)((const char*)(gbase) + (voff)[_i]), (LAS unsigned*)(lds + (bufoff) + ldsw + _i * 8192), 16, 0, 0); } while (0)
; #define PG8_LDA(dst, b, h) do { _Pragma("unroll") for (int m = 0; m < 4; ++m) _Pragma("unroll") for (int k = 0; k < 2; ++k) dst[m][k] = *(const LAS bf16x8*)(lds + PG8_SA(b, h) + aoff + m * 2048 + k * 1024); } while (0)
; #define PG8_LDB(dst, b, h) do { _Pragma("unroll") for (int n = 0; n < 2; ++n) _Pragma("unroll") for (int k = 0; k < 2; ++k) dst[n][k] = *(const LAS bf16x8*)(lds + PG8_SB(b, h) + boff + n * 2048 + k * 1024); } while (0)
; #define PG8_MMA(ai, bj, At, Bt) do { __builtin_amdgcn_s_setprio(1); _Pragma("unroll") for (int m = 0; m < 4; ++m) _Pragma("unroll") for (int n = 0; n < 2; ++n) _Pragma("unroll") for (int k = 0; k < 2; ++k) \
;         acc[ai][bj][m][n] = __builtin_amdgcn_mfma_f32_16x16x32_bf16(Bt[n][k], At[m][k], acc[ai][bj][m][n], 0, 0, 0); __builtin_amdgcn_s_setprio(0); } while (0)
; #define PG8_WAIT_V(n) asm volatile("s_waitcnt vmcnt(" #n ")" ::: "memory")
; template <class Epi, class Sched>
; DI void gemm_phase(LAS unsigned char* lds, const Gemm g, const Sched& S, const Epi& E) {
;     ...
;             PG8_LDB(B0, 0, 0); PG8_SCHED; PG8_LDA(At, 0, 0); PG8_STAGE(PG8_SA(1, 1), a1 + hstep, voffA);
;             PG8_WAIT_L(8); PG8_BAR; PG8_WAIT_L(0); PG8_MMA(0, 0, At, B0); PG8_BAR; PG8_SCHED;
;             PG8_LDB(B1, 0, 1); PG8_STAGE(PG8_SB(0, 0), b2, voffB);
;             PG8_BAR; PG8_WAIT_L(0); PG8_MMA(0, 1, At, B1); PG8_BAR;
;             PG8_LDA(At, 0, 1); PG8_STAGE(PG8_SA(0, 0), a2, voffA);
;             PG8_BAR; PG8_WAIT_L(0); PG8_MMA(1, 0, At, B0); PG8_BAR; PG8_SCHED;
;             PG8_STAGE(PG8_SB(0, 1), b2 + hstep, voffB);
;             PG8_WAIT_V(6); PG8_BAR; PG8_MMA(1, 1, At, B1); PG8_BAR;
;             PG8_LDB(B0, 1, 0); PG8_SCHED; PG8_LDA(At, 1, 0); PG8_STAGE(PG8_SA(0, 1), a2 + hstep, voffA);
;             PG8_WAIT_L(8); PG8_BAR; PG8_WAIT_L(0); PG8_MMA(0, 0, At, B0); PG8_BAR; PG8_SCHED;
;             PG8_LDB(B1, 1, 1); PG8_STAGE(PG8_SB(1, 0), b3, voffB);
;             PG8_BAR; PG8_WAIT_L(0); PG8_MMA(0, 1, At, B1); PG8_BAR;
;             PG8_LDA(At, 1, 1); PG8_STAGE(PG8_SA(1, 0), a3, voffA);
;             PG8_BAR; PG8_WAIT_L(0); PG8_MMA(1, 0, At, B0); PG8_BAR; PG8_SCHED;
.LBB0_1523:
	ds_read_b128 v[140:143], v146
	ds_read_b128 v[150:153], v146 offset:1024
	ds_read_b128 v[154:157], v146 offset:2048
	ds_read_b128 v[158:161], v146 offset:3072
	s_add_u32 s50, s42, 0xfff80080
	s_addc_u32 s51, s43, -1
	s_cmp_eq_u32 s73, 28
	s_cselect_b32 s53, s67, s51
	s_cselect_b32 s52, s68, s50
	s_cselect_b32 s51, s69, s72
	s_cselect_b32 s50, s70, s71
	v_lshl_add_u64 v[202:203], s[42:43], 0, v[136:137]
	s_add_i32 m0, s47, 0xc000
	ds_read_b128 v[168:171], v147
	ds_read_b128 v[172:175], v147 offset:1024
	ds_read_b128 v[176:179], v147 offset:2048
	ds_read_b128 v[180:183], v147 offset:3072
	ds_read_b128 v[184:187], v147 offset:4096
	ds_read_b128 v[188:191], v147 offset:5120
	ds_read_b128 v[192:195], v147 offset:6144
	ds_read_b128 v[198:201], v147 offset:7168
	global_load_lds_dwordx4 v[202:203], off
	v_lshl_add_u64 v[202:203], s[42:43], 0, v[138:139]
	s_add_i32 m0, s47, 0xe000
	s_nop 0
	global_load_lds_dwordx4 v[202:203], off
	s_waitcnt lgkmcnt(8)
	s_barrier
	s_waitcnt lgkmcnt(0)
	s_setprio 1
	s_waitcnt lgkmcnt(0)
	v_mfma_f32_16x16x32_bf16 v[126:129], v[140:143], v[168:171], v[126:129]
	v_mfma_f32_16x16x32_bf16 v[122:125], v[154:157], v[168:171], v[122:125]
	v_mfma_f32_16x16x32_bf16 v[110:113], v[140:143], v[176:179], v[110:113]
	v_mfma_f32_16x16x32_bf16 v[106:109], v[154:157], v[176:179], v[106:109]
	v_mfma_f32_16x16x32_bf16 v[94:97], v[140:143], v[184:187], v[94:97]
	v_mfma_f32_16x16x32_bf16 v[90:93], v[154:157], v[184:187], v[90:93]
	v_mfma_f32_16x16x32_bf16 v[78:81], v[140:143], v[192:195], v[78:81]
	v_mfma_f32_16x16x32_bf16 v[74:77], v[154:157], v[192:195], v[74:77]
	v_mfma_f32_16x16x32_bf16 v[126:129], v[150:153], v[172:175], v[126:129]
	v_mfma_f32_16x16x32_bf16 v[122:125], v[158:161], v[172:175], v[122:125]
	v_mfma_f32_16x16x32_bf16 v[110:113], v[150:153], v[180:183], v[110:113]
	v_mfma_f32_16x16x32_bf16 v[106:109], v[158:161], v[180:183], v[106:109]
	v_mfma_f32_16x16x32_bf16 v[94:97], v[150:153], v[188:191], v[94:97]
	v_mfma_f32_16x16x32_bf16 v[90:93], v[158:161], v[188:191], v[90:93]
	v_mfma_f32_16x16x32_bf16 v[78:81], v[150:153], v[198:201], v[78:81]
	v_mfma_f32_16x16x32_bf16 v[74:77], v[158:161], v[198:201], v[74:77]
	s_setprio 0
	s_barrier
	s_add_i32 s83, s63, s33
	v_lshl_add_u64 v[218:219], s[50:51], 0, v[132:133]
	s_mov_b32 m0, s83
	ds_read_b128 v[202:205], v148
	ds_read_b128 v[206:209], v148 offset:1024
	ds_read_b128 v[210:213], v148 offset:2048
	ds_read_b128 v[214:217], v148 offset:3072
	global_load_lds_dwordx4 v[218:219], off
	v_lshl_add_u64 v[220:221], s[50:51], 0, v[130:131]
	s_add_i32 m0, s83, 0x2000
	s_nop 0
	global_load_lds_dwordx4 v[220:221], off
	s_barrier
	s_waitcnt lgkmcnt(0)
	s_setprio 1
	s_waitcnt lgkmcnt(0)
	v_mfma_f32_16x16x32_bf16 v[118:121], v[202:205], v[168:171], v[118:121]
	v_mfma_f32_16x16x32_bf16 v[114:117], v[210:213], v[168:171], v[114:117]
	v_mfma_f32_16x16x32_bf16 v[102:105], v[202:205], v[176:179], v[102:105]
	v_mfma_f32_16x16x32_bf16 v[98:101], v[210:213], v[176:179], v[98:101]
	v_mfma_f32_16x16x32_bf16 v[86:89], v[202:205], v[184:187], v[86:89]
	v_mfma_f32_16x16x32_bf16 v[82:85], v[210:213], v[184:187], v[82:85]
	v_mfma_f32_16x16x32_bf16 v[70:73], v[202:205], v[192:195], v[70:73]
	v_mfma_f32_16x16x32_bf16 v[66:69], v[210:213], v[192:195], v[66:69]
	v_mfma_f32_16x16x32_bf16 v[118:121], v[206:209], v[172:175], v[118:121]
	v_mfma_f32_16x16x32_bf16 v[114:117], v[214:217], v[172:175], v[114:117]
	v_mfma_f32_16x16x32_bf16 v[102:105], v[206:209], v[180:183], v[102:105]
	v_mfma_f32_16x16x32_bf16 v[98:101], v[214:217], v[180:183], v[98:101]
	v_mfma_f32_16x16x32_bf16 v[86:89], v[206:209], v[188:191], v[86:89]
	v_mfma_f32_16x16x32_bf16 v[82:85], v[214:217], v[188:191], v[82:85]
	v_mfma_f32_16x16x32_bf16 v[70:73], v[206:209], v[198:201], v[70:73]
	v_mfma_f32_16x16x32_bf16 v[66:69], v[214:217], v[198:201], v[66:69]
	s_setprio 0
	s_mov_b32 m0, s47
	v_lshl_add_u64 v[222:223], s[52:53], 0, v[132:133]
	s_barrier
	ds_read_b128 v[168:171], v147 offset:16384
	ds_read_b128 v[172:175], v147 offset:17408
	ds_read_b128 v[176:179], v147 offset:18432
	ds_read_b128 v[180:183], v147 offset:19456
	ds_read_b128 v[184:187], v147 offset:20480
	ds_read_b128 v[188:191], v147 offset:21504
	ds_read_b128 v[192:195], v147 offset:22528
	ds_read_b128 v[198:201], v147 offset:23552
	global_load_lds_dwordx4 v[222:223], off
	v_lshl_add_u64 v[224:225], s[52:53], 0, v[130:131]
	s_mov_b32 m0, s54
	s_nop 0
	global_load_lds_dwordx4 v[224:225], off
	s_barrier
	s_waitcnt lgkmcnt(0)
	s_setprio 1
	s_waitcnt lgkmcnt(0)
	v_mfma_f32_16x16x32_bf16 v[62:65], v[140:143], v[168:171], v[62:65]
	v_mfma_f32_16x16x32_bf16 v[58:61], v[154:157], v[168:171], v[58:61]
	v_mfma_f32_16x16x32_bf16 v[46:49], v[140:143], v[176:179], v[46:49]
	v_mfma_f32_16x16x32_bf16 v[42:45], v[154:157], v[176:179], v[42:45]
	v_mfma_f32_16x16x32_bf16 v[30:33], v[140:143], v[184:187], v[30:33]
	v_mfma_f32_16x16x32_bf16 v[26:29], v[154:157], v[184:187], v[26:29]
	v_mfma_f32_16x16x32_bf16 v[14:17], v[140:143], v[192:195], v[14:17]
	v_mfma_f32_16x16x32_bf16 v[10:13], v[154:157], v[192:195], v[10:13]
	v_mfma_f32_16x16x32_bf16 v[62:65], v[150:153], v[172:175], v[62:65]
	v_mfma_f32_16x16x32_bf16 v[58:61], v[158:161], v[172:175], v[58:61]
	v_mfma_f32_16x16x32_bf16 v[46:49], v[150:153], v[180:183], v[46:49]
	v_mfma_f32_16x16x32_bf16 v[42:45], v[158:161], v[180:183], v[42:45]
	v_mfma_f32_16x16x32_bf16 v[30:33], v[150:153], v[188:191], v[30:33]
	v_mfma_f32_16x16x32_bf16 v[26:29], v[158:161], v[188:191], v[26:29]
	v_mfma_f32_16x16x32_bf16 v[14:17], v[150:153], v[198:201], v[14:17]
	v_mfma_f32_16x16x32_bf16 v[10:13], v[158:161], v[198:201], v[10:13]
	s_setprio 0
	s_barrier
; #define PG8_STAGE(bufoff, gbase, voff) do { _Pragma("unroll") for (int _i = 0; _i < 2; ++_i) \
;         __builtin_amdgcn_global_load_lds((const unsigned*)((const char*)(gbase) + (voff)[_i]), (LAS unsigned*)(lds + (bufoff) + ldsw + _i * 8192), 16, 0, 0); } while (0)
; #define PG8_LDA(dst, b, h) do { _Pragma("unroll") for (int m = 0; m < 4; ++m) _Pragma("unroll") for (int k = 0; k < 2; ++k) dst[m][k] = *(const LAS bf16x8*)(lds + PG8_SA(b, h) + aoff + m * 2048 + k * 1024); } while (0)
; #define PG8_LDB(dst, b, h) do { _Pragma("unroll") for (int n = 0; n < 2; ++n) _Pragma("unroll") for (int k = 0; k < 2; ++k) dst[n][k] = *(const LAS bf16x8*)(lds + PG8_SB(b, h) + boff + n * 2048 + k * 1024); } while (0)
; #define PG8_MMA(ai, bj, At, Bt) do { __builtin_amdgcn_s_setprio(1); _Pragma("unroll") for (int m = 0; m < 4; ++m) _Pragma("unroll") for (int n = 0; n < 2; ++n) _Pragma("unroll") for (int k = 0; k < 2; ++k) \
;         acc[ai][bj][m][n] = __builtin_amdgcn_mfma_f32_16x16x32_bf16(Bt[n][k], At[m][k], acc[ai][bj][m][n], 0, 0, 0); __builtin_amdgcn_s_setprio(0); } while (0)
; #define PG8_WAIT_V(n) asm volatile("s_waitcnt vmcnt(" #n ")" ::: "memory")
; #define PG8_WAIT_L(n) asm volatile("s_waitcnt lgkmcnt(" #n ")" ::: "memory")
; #define PG8_BAR __builtin_amdgcn_s_barrier()
; #define PG8_SCHED __builtin_amdgcn_sched_barrier(0)
; template <class Epi, class Sched>
; DI void gemm_phase(LAS unsigned char* lds, const Gemm g, const Sched& S, const Epi& E) {
;     ...
;             PG8_STAGE(PG8_SB(0, 1), b2 + hstep, voffB);
;             PG8_WAIT_V(6); PG8_BAR; PG8_MMA(1, 1, At, B1); PG8_BAR;
;             PG8_LDB(B0, 1, 0); PG8_SCHED; PG8_LDA(At, 1, 0); PG8_STAGE(PG8_SA(0, 1), a2 + hstep, voffA);
;             PG8_WAIT_L(8); PG8_BAR; PG8_WAIT_L(0); PG8_MMA(0, 0, At, B0); PG8_BAR; PG8_SCHED;
;             PG8_LDB(B1, 1, 1); PG8_STAGE(PG8_SB(1, 0), b3, voffB);
;             PG8_BAR; PG8_WAIT_L(0); PG8_MMA(0, 1, At, B1); PG8_BAR;
;             PG8_LDA(At, 1, 1); PG8_STAGE(PG8_SA(1, 0), a3, voffA);
;             PG8_BAR; PG8_WAIT_L(0); PG8_MMA(1, 0, At, B0); PG8_BAR; PG8_SCHED;
	s_add_u32 s88, s50, 0x80000
	s_addc_u32 s89, s51, 0
	s_add_i32 s83, s64, s33
	v_lshl_add_u64 v[140:141], s[88:89], 0, v[132:133]
	s_mov_b32 m0, s83
	s_nop 0
	global_load_lds_dwordx4 v[140:141], off
	v_lshl_add_u64 v[140:141], s[88:89], 0, v[130:131]
	s_add_i32 m0, s83, 0x2000
	s_nop 0
	global_load_lds_dwordx4 v[140:141], off
	s_waitcnt vmcnt(6)
	s_barrier
	s_setprio 1
	v_mfma_f32_16x16x32_bf16 v[54:57], v[202:205], v[168:171], v[54:57]
	v_mfma_f32_16x16x32_bf16 v[50:53], v[210:213], v[168:171], v[50:53]
	v_mfma_f32_16x16x32_bf16 v[38:41], v[202:205], v[176:179], v[38:41]
	v_mfma_f32_16x16x32_bf16 v[34:37], v[210:213], v[176:179], v[34:37]
	v_mfma_f32_16x16x32_bf16 v[22:25], v[202:205], v[184:187], v[22:25]
	v_mfma_f32_16x16x32_bf16 v[18:21], v[210:213], v[184:187], v[18:21]
	v_mfma_f32_16x16x32_bf16 v[6:9], v[202:205], v[192:195], v[6:9]
	v_mfma_f32_16x16x32_bf16 v[2:5], v[210:213], v[192:195], v[2:5]
	v_mfma_f32_16x16x32_bf16 v[54:57], v[206:209], v[172:175], v[54:57]
	v_mfma_f32_16x16x32_bf16 v[50:53], v[214:217], v[172:175], v[50:53]
	v_mfma_f32_16x16x32_bf16 v[38:41], v[206:209], v[180:183], v[38:41]
	v_mfma_f32_16x16x32_bf16 v[34:37], v[214:217], v[180:183], v[34:37]
	v_mfma_f32_16x16x32_bf16 v[22:25], v[206:209], v[188:191], v[22:25]
	v_mfma_f32_16x16x32_bf16 v[18:21], v[214:217], v[188:191], v[18:21]
	v_mfma_f32_16x16x32_bf16 v[6:9], v[206:209], v[198:201], v[6:9]
	v_mfma_f32_16x16x32_bf16 v[2:5], v[214:217], v[198:201], v[2:5]
	s_setprio 0
	s_add_i32 s83, 0, 0x18000
	v_add_u32_e32 v134, s83, v145
	s_barrier
	ds_read_b128 v[140:143], v134
	ds_read_b128 v[150:153], v134 offset:1024
	ds_read_b128 v[154:157], v134 offset:2048
	ds_read_b128 v[158:161], v134 offset:3072
	s_add_u32 s52, s52, 0x80000
	s_addc_u32 s53, s53, 0
	s_mov_b32 m0, s55
	v_lshl_add_u64 v[202:203], s[52:53], 0, v[132:133]
	ds_read_b128 v[168:171], v147 offset:32768
	ds_read_b128 v[172:175], v147 offset:33792
	ds_read_b128 v[176:179], v147 offset:34816
	ds_read_b128 v[180:183], v147 offset:35840
	ds_read_b128 v[184:187], v147 offset:36864
	ds_read_b128 v[188:191], v147 offset:37888
	ds_read_b128 v[192:195], v147 offset:38912
	ds_read_b128 v[198:201], v147 offset:39936
	global_load_lds_dwordx4 v[202:203], off
	v_lshl_add_u64 v[202:203], s[52:53], 0, v[130:131]
	s_mov_b32 m0, s57
	s_nop 0
	global_load_lds_dwordx4 v[202:203], off
	s_waitcnt lgkmcnt(8)
	s_barrier
	s_waitcnt lgkmcnt(0)
	s_setprio 1
	s_waitcnt lgkmcnt(0)
	v_mfma_f32_16x16x32_bf16 v[126:129], v[140:143], v[168:171], v[126:129]
	v_mfma_f32_16x16x32_bf16 v[122:125], v[154:157], v[168:171], v[122:125]
	v_mfma_f32_16x16x32_bf16 v[110:113], v[140:143], v[176:179], v[110:113]
	v_mfma_f32_16x16x32_bf16 v[106:109], v[154:157], v[176:179], v[106:109]
	v_mfma_f32_16x16x32_bf16 v[94:97], v[140:143], v[184:187], v[94:97]
	v_mfma_f32_16x16x32_bf16 v[90:93], v[154:157], v[184:187], v[90:93]
	v_mfma_f32_16x16x32_bf16 v[78:81], v[140:143], v[192:195], v[78:81]
	v_mfma_f32_16x16x32_bf16 v[74:77], v[154:157], v[192:195], v[74:77]
	v_mfma_f32_16x16x32_bf16 v[126:129], v[150:153], v[172:175], v[126:129]
	v_mfma_f32_16x16x32_bf16 v[122:125], v[158:161], v[172:175], v[122:125]
	v_mfma_f32_16x16x32_bf16 v[110:113], v[150:153], v[180:183], v[110:113]
	v_mfma_f32_16x16x32_bf16 v[106:109], v[158:161], v[180:183], v[106:109]
	v_mfma_f32_16x16x32_bf16 v[94:97], v[150:153], v[188:191], v[94:97]
	v_mfma_f32_16x16x32_bf16 v[90:93], v[158:161], v[188:191], v[90:93]
	v_mfma_f32_16x16x32_bf16 v[78:81], v[150:153], v[198:201], v[78:81]
	v_mfma_f32_16x16x32_bf16 v[74:77], v[158:161], v[198:201], v[74:77]
	s_setprio 0
	s_barrier
	s_add_i32 s52, 0, 0x1c000
	s_add_i32 s53, s83, s33
	v_add_u32_e32 v134, s52, v145
	v_lshl_add_u64 v[218:219], v[218:219], 0, s[10:11]
	s_mov_b32 m0, s53
	ds_read_b128 v[202:205], v134
	ds_read_b128 v[206:209], v134 offset:1024
	ds_read_b128 v[210:213], v134 offset:2048
	ds_read_b128 v[214:217], v134 offset:3072
	global_load_lds_dwordx4 v[218:219], off
	v_lshl_add_u64 v[218:219], v[220:221], 0, s[10:11]
	s_add_i32 m0, s53, 0x2000
	s_nop 0
	global_load_lds_dwordx4 v[218:219], off
	s_barrier
	s_waitcnt lgkmcnt(0)
	s_setprio 1
	s_waitcnt lgkmcnt(0)
	v_mfma_f32_16x16x32_bf16 v[118:121], v[202:205], v[168:171], v[118:121]
	v_mfma_f32_16x16x32_bf16 v[114:117], v[210:213], v[168:171], v[114:117]
	v_mfma_f32_16x16x32_bf16 v[102:105], v[202:205], v[176:179], v[102:105]
	v_mfma_f32_16x16x32_bf16 v[98:101], v[210:213], v[176:179], v[98:101]
	v_mfma_f32_16x16x32_bf16 v[86:89], v[202:205], v[184:187], v[86:89]
	v_mfma_f32_16x16x32_bf16 v[82:85], v[210:213], v[184:187], v[82:85]
	v_mfma_f32_16x16x32_bf16 v[70:73], v[202:205], v[192:195], v[70:73]
	v_mfma_f32_16x16x32_bf16 v[66:69], v[210:213], v[192:195], v[66:69]
	v_mfma_f32_16x16x32_bf16 v[118:121], v[206:209], v[172:175], v[118:121]
	v_mfma_f32_16x16x32_bf16 v[114:117], v[214:217], v[172:175], v[114:117]
	v_mfma_f32_16x16x32_bf16 v[102:105], v[206:209], v[180:183], v[102:105]
	v_mfma_f32_16x16x32_bf16 v[98:101], v[214:217], v[180:183], v[98:101]
	v_mfma_f32_16x16x32_bf16 v[86:89], v[206:209], v[188:191], v[86:89]
	v_mfma_f32_16x16x32_bf16 v[82:85], v[214:217], v[188:191], v[82:85]
	v_mfma_f32_16x16x32_bf16 v[70:73], v[206:209], v[198:201], v[70:73]
	v_mfma_f32_16x16x32_bf16 v[66:69], v[214:217], v[198:201], v[66:69]
	s_setprio 0
	s_mov_b32 m0, s59
	v_lshl_add_u64 v[218:219], v[222:223], 0, s[10:11]
	s_barrier
	ds_read_b128 v[168:171], v147 offset:49152
	ds_read_b128 v[172:175], v147 offset:50176
	ds_read_b128 v[176:179], v147 offset:51200
	ds_read_b128 v[180:183], v147 offset:52224
	ds_read_b128 v[184:187], v147 offset:53248
	ds_read_b128 v[188:191], v147 offset:54272
	ds_read_b128 v[192:195], v147 offset:55296
	ds_read_b128 v[198:201], v147 offset:56320
	global_load_lds_dwordx4 v[218:219], off
	v_lshl_add_u64 v[218:219], v[224:225], 0, s[10:11]
	s_mov_b32 m0, s62
	s_nop 0
	global_load_lds_dwordx4 v[218:219], off
	s_barrier
; DI float bflo(unsigned u) { return __uint_as_float(u << 16); }
; DI float bfhi(unsigned u) { return __uint_as_float(u & 0xffff0000u); }
; #define PG8_STAGE(bufoff, gbase, voff) do { _Pragma("unroll") for (int _i = 0; _i < 2; ++_i) \
;         __builtin_amdgcn_global_load_lds((const unsigned*)((const char*)(gbase) + (voff)[_i]), (LAS unsigned*)(lds + (bufoff) + ldsw + _i * 8192), 16, 0, 0); } while (0)
; #define PG8_MMA(ai, bj, At, Bt) do { __builtin_amdgcn_s_setprio(1); _Pragma("unroll") for (int m = 0; m < 4; ++m) _Pragma("unroll") for (int n = 0; n < 2; ++n) _Pragma("unroll") for (int k = 0; k < 2; ++k) \
;         acc[ai][bj][m][n] = __builtin_amdgcn_mfma_f32_16x16x32_bf16(Bt[n][k], At[m][k], acc[ai][bj][m][n], 0, 0, 0); __builtin_amdgcn_s_setprio(0); } while (0)
; #define PG8_WAIT_V(n) asm volatile("s_waitcnt vmcnt(" #n ")" ::: "memory")
; #define PG8_WAIT_L(n) asm volatile("s_waitcnt lgkmcnt(" #n ")" ::: "memory")
; #define PG8_BAR __builtin_amdgcn_s_barrier()
; #define PG8_SCHED __builtin_amdgcn_sched_barrier(0)
;     DI void operator()(const f32x4 (&acc)[2][2][4][2], const Unit& u, int wr, int wc, int fr, int fq) const {
;         const int row0 = u.pm * BM + wr * 64 + fr, col0 = u.pn * BM + wc * 32 + 4 * fq;
; #pragma unroll
;         for (int ai = 0; ai < 2; ++ai)
; #pragma unroll
;             for (int m = 0; m < 4; ++m) { const size_t o = (size_t)(row0 + ai * HALF + m * 16) * 1024 + col0;
; #pragma unroll
;                 for (int bj = 0; bj < 2; ++bj)
; #pragma unroll
;                     for (int n = 0; n < 2; ++n) { const size_t oo = o + bj * HALF + n * 16; f32x4 rv;
;                         if (RES_BF16) { const u32x2 t = *(const u32x2*)((const bf16_t*)res + oo); rv = (f32x4){bflo(t.x), bfhi(t.x), bflo(t.y), bfhi(t.y)}; }
; template <class Epi, class Sched>
; DI void gemm_phase(LAS unsigned char* lds, const Gemm g, const Sched& S, const Epi& E) {
;     ...
;             PG8_BAR; PG8_WAIT_L(0); PG8_MMA(1, 0, At, B0); PG8_BAR; PG8_SCHED;
;             PG8_STAGE(PG8_SB(1, 1), b3 + hstep, voffB);
;             PG8_WAIT_V(6); PG8_BAR; PG8_MMA(1, 1, At, B1); PG8_BAR;
	s_waitcnt lgkmcnt(0)
	s_setprio 1
	s_waitcnt lgkmcnt(0)
	v_mfma_f32_16x16x32_bf16 v[62:65], v[140:143], v[168:171], v[62:65]
	v_mfma_f32_16x16x32_bf16 v[58:61], v[154:157], v[168:171], v[58:61]
	v_mfma_f32_16x16x32_bf16 v[46:49], v[140:143], v[176:179], v[46:49]
	v_mfma_f32_16x16x32_bf16 v[42:45], v[154:157], v[176:179], v[42:45]
	v_mfma_f32_16x16x32_bf16 v[30:33], v[140:143], v[184:187], v[30:33]
	v_mfma_f32_16x16x32_bf16 v[26:29], v[154:157], v[184:187], v[26:29]
	v_mfma_f32_16x16x32_bf16 v[14:17], v[140:143], v[192:195], v[14:17]
	v_mfma_f32_16x16x32_bf16 v[10:13], v[154:157], v[192:195], v[10:13]
	v_mfma_f32_16x16x32_bf16 v[62:65], v[150:153], v[172:175], v[62:65]
	v_mfma_f32_16x16x32_bf16 v[58:61], v[158:161], v[172:175], v[58:61]
	v_mfma_f32_16x16x32_bf16 v[46:49], v[150:153], v[180:183], v[46:49]
	v_mfma_f32_16x16x32_bf16 v[42:45], v[158:161], v[180:183], v[42:45]
	v_mfma_f32_16x16x32_bf16 v[30:33], v[150:153], v[188:191], v[30:33]
	v_mfma_f32_16x16x32_bf16 v[26:29], v[158:161], v[188:191], v[26:29]
	v_mfma_f32_16x16x32_bf16 v[14:17], v[150:153], v[198:201], v[14:17]
	v_mfma_f32_16x16x32_bf16 v[10:13], v[158:161], v[198:201], v[10:13]
	s_setprio 0
	s_barrier
	s_add_u32 s50, s50, 0x80080
	s_addc_u32 s51, s51, 0
	s_add_i32 s52, s52, s33
	v_lshl_add_u64 v[140:141], s[50:51], 0, v[132:133]
	s_mov_b32 m0, s52
	s_nop 0
	global_load_lds_dwordx4 v[140:141], off
	v_lshl_add_u64 v[140:141], s[50:51], 0, v[130:131]
	s_add_i32 m0, s52, 0x2000
	s_nop 0
	global_load_lds_dwordx4 v[140:141], off
	s_waitcnt vmcnt(6)
	s_barrier
	s_setprio 1
	v_mfma_f32_16x16x32_bf16 v[54:57], v[202:205], v[168:171], v[54:57]
	v_mfma_f32_16x16x32_bf16 v[50:53], v[210:213], v[168:171], v[50:53]
	v_mfma_f32_16x16x32_bf16 v[38:41], v[202:205], v[176:179], v[38:41]
	v_mfma_f32_16x16x32_bf16 v[34:37], v[210:213], v[176:179], v[34:37]
	v_mfma_f32_16x16x32_bf16 v[22:25], v[202:205], v[184:187], v[22:25]
	v_mfma_f32_16x16x32_bf16 v[18:21], v[210:213], v[184:187], v[18:21]
	v_mfma_f32_16x16x32_bf16 v[6:9], v[202:205], v[192:195], v[6:9]
	v_mfma_f32_16x16x32_bf16 v[2:5], v[210:213], v[192:195], v[2:5]
	v_mfma_f32_16x16x32_bf16 v[54:57], v[206:209], v[172:175], v[54:57]
	v_mfma_f32_16x16x32_bf16 v[50:53], v[214:217], v[172:175], v[50:53]
	v_mfma_f32_16x16x32_bf16 v[38:41], v[206:209], v[180:183], v[38:41]
	v_mfma_f32_16x16x32_bf16 v[34:37], v[214:217], v[180:183], v[34:37]
	v_mfma_f32_16x16x32_bf16 v[22:25], v[206:209], v[188:191], v[22:25]
	v_mfma_f32_16x16x32_bf16 v[18:21], v[214:217], v[188:191], v[18:21]
	v_mfma_f32_16x16x32_bf16 v[6:9], v[206:209], v[198:201], v[6:9]
	v_mfma_f32_16x16x32_bf16 v[2:5], v[214:217], v[198:201], v[2:5]
	s_setprio 0
	s_add_i32 s73, s73, 2
	s_add_u32 s42, s42, 0x100
	s_addc_u32 s43, s43, 0
	s_add_u32 s71, s71, 0x100
	s_addc_u32 s72, s72, 0
	s_cmp_gt_u32 s73, 29
	s_barrier
	s_cbranch_scc0 .LBB0_1523
	v_lshl_add_u32 v236, s56, 8, v144
	v_lshl_or_b32 v237, s84, 9, v149
	v_lshl_or_b32 v236, v236, 11, v237
	v_mov_b32_e32 v228, v236
	v_add_u32_e32 v229, 0x8000, v236
	v_add_u32_e32 v230, 0x10000, v236
	v_add_u32_e32 v231, 0x18000, v236
	v_add_u32_e32 v232, 0x40000, v236
	v_add_u32_e32 v233, 0x48000, v236
	v_add_u32_e32 v234, 0x50000, v236
	v_add_u32_e32 v235, 0x58000, v236
	v_and_b32_e32 v248, 63, v1
	v_lshrrev_b32_e32 v249, 3, v248
	v_and_b32_e32 v250, 3, v248
	v_lshl_or_b32 v250, v250, 4, v249
	v_lshlrev_b32_e32 v244, 2, v250
	v_add_u32_e32 v245, 32, v244
	v_and_b32_e32 v250, 0xffffffc0, v144
	v_add_u32_e32 v250, v250, v249
	v_lshl_add_u32 v250, s56, 8, v250
	v_mul_u32_u24_e32 v250, 0x800, v250
	v_and_b32_e32 v247, 0xffffffc0, v149
	v_lshl_or_b32 v247, s84, 9, v247
	v_and_b32_e32 v248, 7, v248
	v_lshl_add_u32 v247, v248, 3, v247
	v_add_u32_e32 v246, v250, v247
	s_mov_b32 s98, 0xf0f0f0f0
	s_mov_b32 s99, 0xf0f0f0f0
	v_and_b32_e32 v253, 63, v1
	v_and_b32_e32 v254, 7, v253
	v_lshrrev_b32_e32 v253, 4, v253
	v_lshl_or_b32 v253, v254, 3, v253
	v_lshlrev_b32_e32 v253, 2, v253
	v_add_u32_e32 v254, 16, v253
	s_mov_b32 vcc_lo, 0xff00ff00
	s_mov_b32 vcc_hi, 0xff00ff00
	v_mov_b32_e32 v251, v246
	global_load_dwordx2 v[140:141], v251, s[48:49]
	global_load_dwordx2 v[150:151], v251, s[48:49] offset:256
	v_add_u32_e32 v252, 0x4000, v246
	global_load_dwordx2 v[142:143], v252, s[48:49]
	global_load_dwordx2 v[152:153], v252, s[48:49] offset:256
	v_add_u32_e32 v251, 0x8000, v246
	global_load_dwordx2 v[154:155], v251, s[48:49]
	global_load_dwordx2 v[158:159], v251, s[48:49] offset:256
	v_add_u32_e32 v252, 0xc000, v246
	global_load_dwordx2 v[156:157], v252, s[48:49]
	global_load_dwordx2 v[160:161], v252, s[48:49] offset:256
	v_add_u32_e32 v251, 0x10000, v246
	global_load_dwordx2 v[168:169], v251, s[48:49]
	global_load_dwordx2 v[172:173], v251, s[48:49] offset:256
	v_add_u32_e32 v252, 0x14000, v246
	global_load_dwordx2 v[170:171], v252, s[48:49]
	global_load_dwordx2 v[174:175], v252, s[48:49] offset:256
	v_add_u32_e32 v251, 0x18000, v246
	global_load_dwordx2 v[176:177], v251, s[48:49]
	global_load_dwordx2 v[180:181], v251, s[48:49] offset:256
	v_add_u32_e32 v252, 0x1c000, v246
	global_load_dwordx2 v[178:179], v252, s[48:49]
	global_load_dwordx2 v[182:183], v252, s[48:49] offset:256
	v_add_u32_e32 v251, 0x40000, v246
	global_load_dwordx2 v[184:185], v251, s[48:49]
	global_load_dwordx2 v[188:189], v251, s[48:49] offset:256
	v_add_u32_e32 v252, 0x44000, v246
	global_load_dwordx2 v[186:187], v252, s[48:49]
	global_load_dwordx2 v[190:191], v252, s[48:49] offset:256
	v_add_u32_e32 v251, 0x48000, v246
	global_load_dwordx2 v[192:193], v251, s[48:49]
	global_load_dwordx2 v[198:199], v251, s[48:49] offset:256
	v_add_u32_e32 v252, 0x4c000, v246
	global_load_dwordx2 v[194:195], v252, s[48:49]
	global_load_dwordx2 v[200:201], v252, s[48:49] offset:256
	v_add_u32_e32 v251, 0x50000, v246
	global_load_dwordx2 v[202:203], v251, s[48:49]
	global_load_dwordx2 v[206:207], v251, s[48:49] offset:256
	v_add_u32_e32 v252, 0x54000, v246
	global_load_dwordx2 v[204:205], v252, s[48:49]
	global_load_dwordx2 v[208:209], v252, s[48:49] offset:256
	v_add_u32_e32 v251, 0x58000, v246
	global_load_dwordx2 v[210:211], v251, s[48:49]
	global_load_dwordx2 v[214:215], v251, s[48:49] offset:256
	v_add_u32_e32 v252, 0x5c000, v246
	global_load_dwordx2 v[212:213], v252, s[48:49]
	global_load_dwordx2 v[216:217], v252, s[48:49] offset:256
	s_waitcnt vmcnt(28)
; DI unsigned pk_bf16(float a, float b) { f32x2 v = {a, b}; bf2_t r = __builtin_convertvector(v, bf2_t); return __builtin_bit_cast(unsigned, r); }
; DI float bflo(unsigned u) { return __uint_as_float(u << 16); }
; DI float bfhi(unsigned u) { return __uint_as_float(u & 0xffff0000u); }
;     DI void operator()(const f32x4 (&acc)[2][2][4][2], const Unit& u, int wr, int wc, int fr, int fq) const {
;         const int row0 = u.pm * BM + wr * 64 + fr, col0 = u.pn * BM + wc * 32 + 4 * fq;
; #pragma unroll
;         for (int ai = 0; ai < 2; ++ai)
; #pragma unroll
;             for (int m = 0; m < 4; ++m) { const size_t o = (size_t)(row0 + ai * HALF + m * 16) * 1024 + col0;
; #pragma unroll
;                 for (int bj = 0; bj < 2; ++bj)
; #pragma unroll
;                     for (int n = 0; n < 2; ++n) { const size_t oo = o + bj * HALF + n * 16; f32x4 rv;
;                         if (RES_BF16) { const u32x2 t = *(const u32x2*)((const bf16_t*)res + oo); rv = (f32x4){bflo(t.x), bfhi(t.x), bflo(t.y), bfhi(t.y)}; }
;                         else rv = *(const f32x4*)((const float*)res + oo);
;                         const f32x4 v = acc[ai][bj][m][n] + rv; u32x2 w; w.x = pk_bf16(v.x, v.y); w.y = pk_bf16(v.z, v.w);
;                         *(u32x2*)(O + oo) = w; } }
	ds_bpermute_b32 v220, v254, v140
	ds_bpermute_b32 v221, v254, v141
	ds_bpermute_b32 v218, v253, v142
	ds_bpermute_b32 v219, v253, v143
	ds_bpermute_b32 v140, v253, v140
	ds_bpermute_b32 v141, v253, v141
	ds_bpermute_b32 v142, v254, v142
	ds_bpermute_b32 v143, v254, v143
	ds_bpermute_b32 v224, v254, v150
	ds_bpermute_b32 v225, v254, v151
	ds_bpermute_b32 v222, v253, v152
	ds_bpermute_b32 v223, v253, v153
	ds_bpermute_b32 v150, v253, v150
	ds_bpermute_b32 v151, v253, v151
	ds_bpermute_b32 v152, v254, v152
	ds_bpermute_b32 v153, v254, v153
	s_waitcnt lgkmcnt(0)
	v_cndmask_b32_e32 v140, v140, v218, vcc
	v_cndmask_b32_e32 v141, v141, v219, vcc
	v_cndmask_b32_e32 v142, v220, v142, vcc
	v_cndmask_b32_e32 v143, v221, v143, vcc
	v_cndmask_b32_e32 v150, v150, v222, vcc
	v_cndmask_b32_e32 v151, v151, v223, vcc
	v_cndmask_b32_e32 v152, v224, v152, vcc
	v_cndmask_b32_e32 v153, v225, v153, vcc
	v_lshlrev_b32_e32 v226, 16, v141
	v_and_b32_e32 v227, 0xffff0000, v141
	v_and_b32_e32 v141, 0xffff0000, v140
	v_lshlrev_b32_e32 v140, 16, v140
	v_pk_add_f32 v[128:129], v[128:129], v[226:227]
	v_pk_add_f32 v[126:127], v[126:127], v[140:141]
	v_lshlrev_b32_e32 v240, 16, v143
	v_and_b32_e32 v241, 0xffff0000, v143
	v_and_b32_e32 v143, 0xffff0000, v142
	v_lshlrev_b32_e32 v142, 16, v142
	v_pk_add_f32 v[124:125], v[124:125], v[240:241]
	v_pk_add_f32 v[122:123], v[122:123], v[142:143]
	v_lshlrev_b32_e32 v226, 16, v151
	v_and_b32_e32 v227, 0xffff0000, v151
	v_and_b32_e32 v151, 0xffff0000, v150
	v_lshlrev_b32_e32 v150, 16, v150
	v_pk_add_f32 v[120:121], v[120:121], v[226:227]
	v_pk_add_f32 v[118:119], v[118:119], v[150:151]
	v_lshlrev_b32_e32 v240, 16, v153
	v_and_b32_e32 v241, 0xffff0000, v153
	v_and_b32_e32 v153, 0xffff0000, v152
	v_lshlrev_b32_e32 v152, 16, v152
	v_pk_add_f32 v[116:117], v[116:117], v[240:241]
	v_pk_add_f32 v[114:115], v[114:115], v[152:153]
	v_cvt_pk_bf16_f32 v126, v126, v127
	v_cvt_pk_bf16_f32 v127, v128, v129
	v_cvt_pk_bf16_f32 v122, v122, v123
	v_cvt_pk_bf16_f32 v123, v124, v125
	v_cvt_pk_bf16_f32 v118, v118, v119
	v_cvt_pk_bf16_f32 v119, v120, v121
	v_cvt_pk_bf16_f32 v114, v114, v115
	v_cvt_pk_bf16_f32 v115, v116, v117
	ds_bpermute_b32 v140, v244, v126
	ds_bpermute_b32 v141, v244, v127
	ds_bpermute_b32 v142, v244, v122
	ds_bpermute_b32 v143, v244, v123
	ds_bpermute_b32 v150, v245, v126
	ds_bpermute_b32 v151, v245, v127
	ds_bpermute_b32 v152, v245, v122
	ds_bpermute_b32 v153, v245, v123
	s_waitcnt lgkmcnt(0)
	v_cndmask_b32_e64 v140, v140, v142, s[98:99]
	v_cndmask_b32_e64 v141, v141, v143, s[98:99]
	v_mov_b32_e32 v142, v246
	global_store_dwordx2 v142, v[140:141], s[8:9]
	v_cndmask_b32_e64 v150, v150, v152, s[98:99]
	v_cndmask_b32_e64 v151, v151, v153, s[98:99]
	v_add_u32_e32 v152, 0x4000, v246
	global_store_dwordx2 v152, v[150:151], s[8:9]
	ds_bpermute_b32 v140, v244, v118
	ds_bpermute_b32 v141, v244, v119
	ds_bpermute_b32 v142, v244, v114
	ds_bpermute_b32 v143, v244, v115
	ds_bpermute_b32 v150, v245, v118
	ds_bpermute_b32 v151, v245, v119
	ds_bpermute_b32 v152, v245, v114
	ds_bpermute_b32 v153, v245, v115
	s_waitcnt lgkmcnt(0)
	v_cndmask_b32_e64 v140, v140, v142, s[98:99]
	v_cndmask_b32_e64 v141, v141, v143, s[98:99]
	v_mov_b32_e32 v142, v246
	global_store_dwordx2 v142, v[140:141], s[8:9] offset:256
	v_cndmask_b32_e64 v150, v150, v152, s[98:99]
	v_cndmask_b32_e64 v151, v151, v153, s[98:99]
	v_add_u32_e32 v152, 0x4000, v246
	global_store_dwordx2 v152, v[150:151], s[8:9] offset:256
	s_waitcnt vmcnt(28)
	ds_bpermute_b32 v220, v254, v154
	ds_bpermute_b32 v221, v254, v155
	ds_bpermute_b32 v218, v253, v156
	ds_bpermute_b32 v219, v253, v157
	ds_bpermute_b32 v154, v253, v154
	ds_bpermute_b32 v155, v253, v155
	ds_bpermute_b32 v156, v254, v156
	ds_bpermute_b32 v157, v254, v157
	ds_bpermute_b32 v224, v254, v158
	ds_bpermute_b32 v225, v254, v159
	ds_bpermute_b32 v222, v253, v160
	ds_bpermute_b32 v223, v253, v161
	ds_bpermute_b32 v158, v253, v158
	ds_bpermute_b32 v159, v253, v159
	ds_bpermute_b32 v160, v254, v160
	ds_bpermute_b32 v161, v254, v161
	s_waitcnt lgkmcnt(0)
	v_cndmask_b32_e32 v154, v154, v218, vcc
	v_cndmask_b32_e32 v155, v155, v219, vcc
	v_cndmask_b32_e32 v156, v220, v156, vcc
	v_cndmask_b32_e32 v157, v221, v157, vcc
	v_cndmask_b32_e32 v158, v158, v222, vcc
	v_cndmask_b32_e32 v159, v159, v223, vcc
	v_cndmask_b32_e32 v160, v224, v160, vcc
	v_cndmask_b32_e32 v161, v225, v161, vcc
	v_lshlrev_b32_e32 v226, 16, v155
	v_and_b32_e32 v227, 0xffff0000, v155
	v_and_b32_e32 v155, 0xffff0000, v154
	v_lshlrev_b32_e32 v154, 16, v154
	v_pk_add_f32 v[112:113], v[112:113], v[226:227]
	v_pk_add_f32 v[110:111], v[110:111], v[154:155]
	v_lshlrev_b32_e32 v240, 16, v157
	v_and_b32_e32 v241, 0xffff0000, v157
	v_and_b32_e32 v157, 0xffff0000, v156
	v_lshlrev_b32_e32 v156, 16, v156
	v_pk_add_f32 v[108:109], v[108:109], v[240:241]
	v_pk_add_f32 v[106:107], v[106:107], v[156:157]
	v_lshlrev_b32_e32 v226, 16, v159
	v_and_b32_e32 v227, 0xffff0000, v159
	v_and_b32_e32 v159, 0xffff0000, v158
	v_lshlrev_b32_e32 v158, 16, v158
	v_pk_add_f32 v[104:105], v[104:105], v[226:227]
	v_pk_add_f32 v[102:103], v[102:103], v[158:159]
	v_lshlrev_b32_e32 v240, 16, v161
	v_and_b32_e32 v241, 0xffff0000, v161
	v_and_b32_e32 v161, 0xffff0000, v160
	v_lshlrev_b32_e32 v160, 16, v160
	v_pk_add_f32 v[100:101], v[100:101], v[240:241]
	v_pk_add_f32 v[98:99], v[98:99], v[160:161]
	v_cvt_pk_bf16_f32 v110, v110, v111
	v_cvt_pk_bf16_f32 v111, v112, v113
	v_cvt_pk_bf16_f32 v106, v106, v107
	v_cvt_pk_bf16_f32 v107, v108, v109
	v_cvt_pk_bf16_f32 v102, v102, v103
	v_cvt_pk_bf16_f32 v103, v104, v105
	v_cvt_pk_bf16_f32 v98, v98, v99
	v_cvt_pk_bf16_f32 v99, v100, v101
	ds_bpermute_b32 v154, v244, v110
	ds_bpermute_b32 v155, v244, v111
	ds_bpermute_b32 v156, v244, v106
	ds_bpermute_b32 v157, v244, v107
	ds_bpermute_b32 v158, v245, v110
	ds_bpermute_b32 v159, v245, v111
	ds_bpermute_b32 v160, v245, v106
	ds_bpermute_b32 v161, v245, v107
	s_waitcnt lgkmcnt(0)
; DI unsigned pk_bf16(float a, float b) { f32x2 v = {a, b}; bf2_t r = __builtin_convertvector(v, bf2_t); return __builtin_bit_cast(unsigned, r); }
; DI float bflo(unsigned u) { return __uint_as_float(u << 16); }
; DI float bfhi(unsigned u) { return __uint_as_float(u & 0xffff0000u); }
;     DI void operator()(const f32x4 (&acc)[2][2][4][2], const Unit& u, int wr, int wc, int fr, int fq) const {
;         const int row0 = u.pm * BM + wr * 64 + fr, col0 = u.pn * BM + wc * 32 + 4 * fq;
; #pragma unroll
;         for (int ai = 0; ai < 2; ++ai)
; #pragma unroll
;             for (int m = 0; m < 4; ++m) { const size_t o = (size_t)(row0 + ai * HALF + m * 16) * 1024 + col0;
; #pragma unroll
;                 for (int bj = 0; bj < 2; ++bj)
; #pragma unroll
;                     for (int n = 0; n < 2; ++n) { const size_t oo = o + bj * HALF + n * 16; f32x4 rv;
;                         if (RES_BF16) { const u32x2 t = *(const u32x2*)((const bf16_t*)res + oo); rv = (f32x4){bflo(t.x), bfhi(t.x), bflo(t.y), bfhi(t.y)}; }
;                         else rv = *(const f32x4*)((const float*)res + oo);
;                         const f32x4 v = acc[ai][bj][m][n] + rv; u32x2 w; w.x = pk_bf16(v.x, v.y); w.y = pk_bf16(v.z, v.w);
;                         *(u32x2*)(O + oo) = w; } }
	v_cndmask_b32_e64 v154, v154, v156, s[98:99]
	v_cndmask_b32_e64 v155, v155, v157, s[98:99]
	v_add_u32_e32 v156, 0x8000, v246
	global_store_dwordx2 v156, v[154:155], s[8:9]
	v_cndmask_b32_e64 v158, v158, v160, s[98:99]
	v_cndmask_b32_e64 v159, v159, v161, s[98:99]
	v_add_u32_e32 v160, 0xc000, v246
	global_store_dwordx2 v160, v[158:159], s[8:9]
	ds_bpermute_b32 v154, v244, v102
	ds_bpermute_b32 v155, v244, v103
	ds_bpermute_b32 v156, v244, v98
	ds_bpermute_b32 v157, v244, v99
	ds_bpermute_b32 v158, v245, v102
	ds_bpermute_b32 v159, v245, v103
	ds_bpermute_b32 v160, v245, v98
	ds_bpermute_b32 v161, v245, v99
	s_waitcnt lgkmcnt(0)
	v_cndmask_b32_e64 v154, v154, v156, s[98:99]
	v_cndmask_b32_e64 v155, v155, v157, s[98:99]
	v_add_u32_e32 v156, 0x8000, v246
	global_store_dwordx2 v156, v[154:155], s[8:9] offset:256
	v_cndmask_b32_e64 v158, v158, v160, s[98:99]
	v_cndmask_b32_e64 v159, v159, v161, s[98:99]
	v_add_u32_e32 v160, 0xc000, v246
	global_store_dwordx2 v160, v[158:159], s[8:9] offset:256
	s_waitcnt vmcnt(28)
	ds_bpermute_b32 v220, v254, v168
	ds_bpermute_b32 v221, v254, v169
	ds_bpermute_b32 v218, v253, v170
	ds_bpermute_b32 v219, v253, v171
	ds_bpermute_b32 v168, v253, v168
	ds_bpermute_b32 v169, v253, v169
	ds_bpermute_b32 v170, v254, v170
	ds_bpermute_b32 v171, v254, v171
	ds_bpermute_b32 v224, v254, v172
	ds_bpermute_b32 v225, v254, v173
	ds_bpermute_b32 v222, v253, v174
	ds_bpermute_b32 v223, v253, v175
	ds_bpermute_b32 v172, v253, v172
	ds_bpermute_b32 v173, v253, v173
	ds_bpermute_b32 v174, v254, v174
	ds_bpermute_b32 v175, v254, v175
	s_waitcnt lgkmcnt(0)
	v_cndmask_b32_e32 v168, v168, v218, vcc
	v_cndmask_b32_e32 v169, v169, v219, vcc
	v_cndmask_b32_e32 v170, v220, v170, vcc
	v_cndmask_b32_e32 v171, v221, v171, vcc
	v_cndmask_b32_e32 v172, v172, v222, vcc
	v_cndmask_b32_e32 v173, v173, v223, vcc
	v_cndmask_b32_e32 v174, v224, v174, vcc
	v_cndmask_b32_e32 v175, v225, v175, vcc
	v_lshlrev_b32_e32 v226, 16, v169
	v_and_b32_e32 v227, 0xffff0000, v169
	v_and_b32_e32 v169, 0xffff0000, v168
	v_lshlrev_b32_e32 v168, 16, v168
	v_pk_add_f32 v[96:97], v[96:97], v[226:227]
	v_pk_add_f32 v[94:95], v[94:95], v[168:169]
	v_lshlrev_b32_e32 v240, 16, v171
	v_and_b32_e32 v241, 0xffff0000, v171
	v_and_b32_e32 v171, 0xffff0000, v170
	v_lshlrev_b32_e32 v170, 16, v170
	v_pk_add_f32 v[92:93], v[92:93], v[240:241]
	v_pk_add_f32 v[90:91], v[90:91], v[170:171]
	v_lshlrev_b32_e32 v226, 16, v173
	v_and_b32_e32 v227, 0xffff0000, v173
	v_and_b32_e32 v173, 0xffff0000, v172
	v_lshlrev_b32_e32 v172, 16, v172
	v_pk_add_f32 v[88:89], v[88:89], v[226:227]
	v_pk_add_f32 v[86:87], v[86:87], v[172:173]
	v_lshlrev_b32_e32 v240, 16, v175
	v_and_b32_e32 v241, 0xffff0000, v175
	v_and_b32_e32 v175, 0xffff0000, v174
	v_lshlrev_b32_e32 v174, 16, v174
	v_pk_add_f32 v[84:85], v[84:85], v[240:241]
	v_pk_add_f32 v[82:83], v[82:83], v[174:175]
	v_cvt_pk_bf16_f32 v94, v94, v95
	v_cvt_pk_bf16_f32 v95, v96, v97
	v_cvt_pk_bf16_f32 v90, v90, v91
	v_cvt_pk_bf16_f32 v91, v92, v93
	v_cvt_pk_bf16_f32 v86, v86, v87
	v_cvt_pk_bf16_f32 v87, v88, v89
	v_cvt_pk_bf16_f32 v82, v82, v83
	v_cvt_pk_bf16_f32 v83, v84, v85
	ds_bpermute_b32 v168, v244, v94
	ds_bpermute_b32 v169, v244, v95
	ds_bpermute_b32 v170, v244, v90
	ds_bpermute_b32 v171, v244, v91
	ds_bpermute_b32 v172, v245, v94
	ds_bpermute_b32 v173, v245, v95
	ds_bpermute_b32 v174, v245, v90
	ds_bpermute_b32 v175, v245, v91
	s_waitcnt lgkmcnt(0)
	v_cndmask_b32_e64 v168, v168, v170, s[98:99]
	v_cndmask_b32_e64 v169, v169, v171, s[98:99]
	v_add_u32_e32 v170, 0x10000, v246
	global_store_dwordx2 v170, v[168:169], s[8:9]
	v_cndmask_b32_e64 v172, v172, v174, s[98:99]
	v_cndmask_b32_e64 v173, v173, v175, s[98:99]
	v_add_u32_e32 v174, 0x14000, v246
	global_store_dwordx2 v174, v[172:173], s[8:9]
	ds_bpermute_b32 v168, v244, v86
	ds_bpermute_b32 v169, v244, v87
	ds_bpermute_b32 v170, v244, v82
	ds_bpermute_b32 v171, v244, v83
	ds_bpermute_b32 v172, v245, v86
	ds_bpermute_b32 v173, v245, v87
	ds_bpermute_b32 v174, v245, v82
	ds_bpermute_b32 v175, v245, v83
	s_waitcnt lgkmcnt(0)
	v_cndmask_b32_e64 v168, v168, v170, s[98:99]
	v_cndmask_b32_e64 v169, v169, v171, s[98:99]
	v_add_u32_e32 v170, 0x10000, v246
	global_store_dwordx2 v170, v[168:169], s[8:9] offset:256
	v_cndmask_b32_e64 v172, v172, v174, s[98:99]
	v_cndmask_b32_e64 v173, v173, v175, s[98:99]
	v_add_u32_e32 v174, 0x14000, v246
	global_store_dwordx2 v174, v[172:173], s[8:9] offset:256
	s_waitcnt vmcnt(28)
	ds_bpermute_b32 v220, v254, v176
	ds_bpermute_b32 v221, v254, v177
	ds_bpermute_b32 v218, v253, v178
	ds_bpermute_b32 v219, v253, v179
	ds_bpermute_b32 v176, v253, v176
	ds_bpermute_b32 v177, v253, v177
	ds_bpermute_b32 v178, v254, v178
	ds_bpermute_b32 v179, v254, v179
	ds_bpermute_b32 v224, v254, v180
	ds_bpermute_b32 v225, v254, v181
	ds_bpermute_b32 v222, v253, v182
	ds_bpermute_b32 v223, v253, v183
	ds_bpermute_b32 v180, v253, v180
	ds_bpermute_b32 v181, v253, v181
	ds_bpermute_b32 v182, v254, v182
	ds_bpermute_b32 v183, v254, v183
	s_waitcnt lgkmcnt(0)
; DI unsigned pk_bf16(float a, float b) { f32x2 v = {a, b}; bf2_t r = __builtin_convertvector(v, bf2_t); return __builtin_bit_cast(unsigned, r); }
; DI float bflo(unsigned u) { return __uint_as_float(u << 16); }
; DI float bfhi(unsigned u) { return __uint_as_float(u & 0xffff0000u); }
;     DI void operator()(const f32x4 (&acc)[2][2][4][2], const Unit& u, int wr, int wc, int fr, int fq) const {
;         const int row0 = u.pm * BM + wr * 64 + fr, col0 = u.pn * BM + wc * 32 + 4 * fq;
; #pragma unroll
;         for (int ai = 0; ai < 2; ++ai)
; #pragma unroll
;             for (int m = 0; m < 4; ++m) { const size_t o = (size_t)(row0 + ai * HALF + m * 16) * 1024 + col0;
; #pragma unroll
;                 for (int bj = 0; bj < 2; ++bj)
; #pragma unroll
;                     for (int n = 0; n < 2; ++n) { const size_t oo = o + bj * HALF + n * 16; f32x4 rv;
;                         if (RES_BF16) { const u32x2 t = *(const u32x2*)((const bf16_t*)res + oo); rv = (f32x4){bflo(t.x), bfhi(t.x), bflo(t.y), bfhi(t.y)}; }
;                         else rv = *(const f32x4*)((const float*)res + oo);
;                         const f32x4 v = acc[ai][bj][m][n] + rv; u32x2 w; w.x = pk_bf16(v.x, v.y); w.y = pk_bf16(v.z, v.w);
;                         *(u32x2*)(O + oo) = w; } }
	v_cndmask_b32_e32 v176, v176, v218, vcc
	v_cndmask_b32_e32 v177, v177, v219, vcc
	v_cndmask_b32_e32 v178, v220, v178, vcc
	v_cndmask_b32_e32 v179, v221, v179, vcc
	v_cndmask_b32_e32 v180, v180, v222, vcc
	v_cndmask_b32_e32 v181, v181, v223, vcc
	v_cndmask_b32_e32 v182, v224, v182, vcc
	v_cndmask_b32_e32 v183, v225, v183, vcc
	v_lshlrev_b32_e32 v226, 16, v177
	v_and_b32_e32 v227, 0xffff0000, v177
	v_and_b32_e32 v177, 0xffff0000, v176
	v_lshlrev_b32_e32 v176, 16, v176
	v_pk_add_f32 v[80:81], v[80:81], v[226:227]
	v_pk_add_f32 v[78:79], v[78:79], v[176:177]
	v_lshlrev_b32_e32 v240, 16, v179
	v_and_b32_e32 v241, 0xffff0000, v179
	v_and_b32_e32 v179, 0xffff0000, v178
	v_lshlrev_b32_e32 v178, 16, v178
	v_pk_add_f32 v[76:77], v[76:77], v[240:241]
	v_pk_add_f32 v[74:75], v[74:75], v[178:179]
	v_lshlrev_b32_e32 v226, 16, v181
	v_and_b32_e32 v227, 0xffff0000, v181
	v_and_b32_e32 v181, 0xffff0000, v180
	v_lshlrev_b32_e32 v180, 16, v180
	v_pk_add_f32 v[72:73], v[72:73], v[226:227]
	v_pk_add_f32 v[70:71], v[70:71], v[180:181]
	v_lshlrev_b32_e32 v240, 16, v183
	v_and_b32_e32 v241, 0xffff0000, v183
	v_and_b32_e32 v183, 0xffff0000, v182
	v_lshlrev_b32_e32 v182, 16, v182
	v_pk_add_f32 v[68:69], v[68:69], v[240:241]
	v_pk_add_f32 v[66:67], v[66:67], v[182:183]
	v_cvt_pk_bf16_f32 v78, v78, v79
	v_cvt_pk_bf16_f32 v79, v80, v81
	v_cvt_pk_bf16_f32 v74, v74, v75
	v_cvt_pk_bf16_f32 v75, v76, v77
	v_cvt_pk_bf16_f32 v70, v70, v71
	v_cvt_pk_bf16_f32 v71, v72, v73
	v_cvt_pk_bf16_f32 v66, v66, v67
	v_cvt_pk_bf16_f32 v67, v68, v69
	ds_bpermute_b32 v176, v244, v78
	ds_bpermute_b32 v177, v244, v79
	ds_bpermute_b32 v178, v244, v74
	ds_bpermute_b32 v179, v244, v75
	ds_bpermute_b32 v180, v245, v78
	ds_bpermute_b32 v181, v245, v79
	ds_bpermute_b32 v182, v245, v74
	ds_bpermute_b32 v183, v245, v75
	s_waitcnt lgkmcnt(0)
	v_cndmask_b32_e64 v176, v176, v178, s[98:99]
	v_cndmask_b32_e64 v177, v177, v179, s[98:99]
	v_add_u32_e32 v178, 0x18000, v246
	global_store_dwordx2 v178, v[176:177], s[8:9]
	v_cndmask_b32_e64 v180, v180, v182, s[98:99]
	v_cndmask_b32_e64 v181, v181, v183, s[98:99]
	v_add_u32_e32 v182, 0x1c000, v246
	global_store_dwordx2 v182, v[180:181], s[8:9]
	ds_bpermute_b32 v176, v244, v70
	ds_bpermute_b32 v177, v244, v71
	ds_bpermute_b32 v178, v244, v66
	ds_bpermute_b32 v179, v244, v67
	ds_bpermute_b32 v180, v245, v70
	ds_bpermute_b32 v181, v245, v71
	ds_bpermute_b32 v182, v245, v66
	ds_bpermute_b32 v183, v245, v67
	s_waitcnt lgkmcnt(0)
	v_cndmask_b32_e64 v176, v176, v178, s[98:99]
	v_cndmask_b32_e64 v177, v177, v179, s[98:99]
	v_add_u32_e32 v178, 0x18000, v246
	global_store_dwordx2 v178, v[176:177], s[8:9] offset:256
	v_cndmask_b32_e64 v180, v180, v182, s[98:99]
	v_cndmask_b32_e64 v181, v181, v183, s[98:99]
	v_add_u32_e32 v182, 0x1c000, v246
	global_store_dwordx2 v182, v[180:181], s[8:9] offset:256
	s_waitcnt vmcnt(28)
	ds_bpermute_b32 v220, v254, v184
	ds_bpermute_b32 v221, v254, v185
	ds_bpermute_b32 v218, v253, v186
	ds_bpermute_b32 v219, v253, v187
	ds_bpermute_b32 v184, v253, v184
	ds_bpermute_b32 v185, v253, v185
	ds_bpermute_b32 v186, v254, v186
	ds_bpermute_b32 v187, v254, v187
	ds_bpermute_b32 v224, v254, v188
	ds_bpermute_b32 v225, v254, v189
	ds_bpermute_b32 v222, v253, v190
	ds_bpermute_b32 v223, v253, v191
	ds_bpermute_b32 v188, v253, v188
	ds_bpermute_b32 v189, v253, v189
	ds_bpermute_b32 v190, v254, v190
	ds_bpermute_b32 v191, v254, v191
	s_waitcnt lgkmcnt(0)
	v_cndmask_b32_e32 v184, v184, v218, vcc
	v_cndmask_b32_e32 v185, v185, v219, vcc
	v_cndmask_b32_e32 v186, v220, v186, vcc
	v_cndmask_b32_e32 v187, v221, v187, vcc
	v_cndmask_b32_e32 v188, v188, v222, vcc
	v_cndmask_b32_e32 v189, v189, v223, vcc
	v_cndmask_b32_e32 v190, v224, v190, vcc
	v_cndmask_b32_e32 v191, v225, v191, vcc
	v_lshlrev_b32_e32 v226, 16, v185
	v_and_b32_e32 v227, 0xffff0000, v185
	v_and_b32_e32 v185, 0xffff0000, v184
	v_lshlrev_b32_e32 v184, 16, v184
	v_pk_add_f32 v[64:65], v[64:65], v[226:227]
	v_pk_add_f32 v[62:63], v[62:63], v[184:185]
	v_lshlrev_b32_e32 v240, 16, v187
	v_and_b32_e32 v241, 0xffff0000, v187
	v_and_b32_e32 v187, 0xffff0000, v186
	v_lshlrev_b32_e32 v186, 16, v186
	v_pk_add_f32 v[60:61], v[60:61], v[240:241]
	v_pk_add_f32 v[58:59], v[58:59], v[186:187]
	v_lshlrev_b32_e32 v226, 16, v189
	v_and_b32_e32 v227, 0xffff0000, v189
	v_and_b32_e32 v189, 0xffff0000, v188
	v_lshlrev_b32_e32 v188, 16, v188
	v_pk_add_f32 v[56:57], v[56:57], v[226:227]
	v_pk_add_f32 v[54:55], v[54:55], v[188:189]
	v_lshlrev_b32_e32 v240, 16, v191
	v_and_b32_e32 v241, 0xffff0000, v191
	v_and_b32_e32 v191, 0xffff0000, v190
	v_lshlrev_b32_e32 v190, 16, v190
	v_pk_add_f32 v[52:53], v[52:53], v[240:241]
	v_pk_add_f32 v[50:51], v[50:51], v[190:191]
	v_cvt_pk_bf16_f32 v62, v62, v63
	v_cvt_pk_bf16_f32 v63, v64, v65
	v_cvt_pk_bf16_f32 v58, v58, v59
	v_cvt_pk_bf16_f32 v59, v60, v61
	v_cvt_pk_bf16_f32 v54, v54, v55
	v_cvt_pk_bf16_f32 v55, v56, v57
	v_cvt_pk_bf16_f32 v50, v50, v51
	v_cvt_pk_bf16_f32 v51, v52, v53
	ds_bpermute_b32 v184, v244, v62
	ds_bpermute_b32 v185, v244, v63
	ds_bpermute_b32 v186, v244, v58
	ds_bpermute_b32 v187, v244, v59
	ds_bpermute_b32 v188, v245, v62
	ds_bpermute_b32 v189, v245, v63
	ds_bpermute_b32 v190, v245, v58
	ds_bpermute_b32 v191, v245, v59
	s_waitcnt lgkmcnt(0)
	v_cndmask_b32_e64 v184, v184, v186, s[98:99]
	v_cndmask_b32_e64 v185, v185, v187, s[98:99]
	v_add_u32_e32 v186, 0x40000, v246
	global_store_dwordx2 v186, v[184:185], s[8:9]
	v_cndmask_b32_e64 v188, v188, v190, s[98:99]
	v_cndmask_b32_e64 v189, v189, v191, s[98:99]
	v_add_u32_e32 v190, 0x44000, v246
	global_store_dwordx2 v190, v[188:189], s[8:9]
	ds_bpermute_b32 v184, v244, v54
	ds_bpermute_b32 v185, v244, v55
	ds_bpermute_b32 v186, v244, v50
	ds_bpermute_b32 v187, v244, v51
	ds_bpermute_b32 v188, v245, v54
	ds_bpermute_b32 v189, v245, v55
	ds_bpermute_b32 v190, v245, v50
	ds_bpermute_b32 v191, v245, v51
	s_waitcnt lgkmcnt(0)
; DI unsigned pk_bf16(float a, float b) { f32x2 v = {a, b}; bf2_t r = __builtin_convertvector(v, bf2_t); return __builtin_bit_cast(unsigned, r); }
; DI float bflo(unsigned u) { return __uint_as_float(u << 16); }
; DI float bfhi(unsigned u) { return __uint_as_float(u & 0xffff0000u); }
;     DI void operator()(const f32x4 (&acc)[2][2][4][2], const Unit& u, int wr, int wc, int fr, int fq) const {
;         const int row0 = u.pm * BM + wr * 64 + fr, col0 = u.pn * BM + wc * 32 + 4 * fq;
; #pragma unroll
;         for (int ai = 0; ai < 2; ++ai)
; #pragma unroll
;             for (int m = 0; m < 4; ++m) { const size_t o = (size_t)(row0 + ai * HALF + m * 16) * 1024 + col0;
; #pragma unroll
;                 for (int bj = 0; bj < 2; ++bj)
; #pragma unroll
;                     for (int n = 0; n < 2; ++n) { const size_t oo = o + bj * HALF + n * 16; f32x4 rv;
;                         if (RES_BF16) { const u32x2 t = *(const u32x2*)((const bf16_t*)res + oo); rv = (f32x4){bflo(t.x), bfhi(t.x), bflo(t.y), bfhi(t.y)}; }
;                         else rv = *(const f32x4*)((const float*)res + oo);
;                         const f32x4 v = acc[ai][bj][m][n] + rv; u32x2 w; w.x = pk_bf16(v.x, v.y); w.y = pk_bf16(v.z, v.w);
;                         *(u32x2*)(O + oo) = w; } }
	v_cndmask_b32_e64 v184, v184, v186, s[98:99]
	v_cndmask_b32_e64 v185, v185, v187, s[98:99]
	v_add_u32_e32 v186, 0x40000, v246
	global_store_dwordx2 v186, v[184:185], s[8:9] offset:256
	v_cndmask_b32_e64 v188, v188, v190, s[98:99]
	v_cndmask_b32_e64 v189, v189, v191, s[98:99]
	v_add_u32_e32 v190, 0x44000, v246
	global_store_dwordx2 v190, v[188:189], s[8:9] offset:256
	s_waitcnt vmcnt(28)
	ds_bpermute_b32 v220, v254, v192
	ds_bpermute_b32 v221, v254, v193
	ds_bpermute_b32 v218, v253, v194
	ds_bpermute_b32 v219, v253, v195
	ds_bpermute_b32 v192, v253, v192
	ds_bpermute_b32 v193, v253, v193
	ds_bpermute_b32 v194, v254, v194
	ds_bpermute_b32 v195, v254, v195
	ds_bpermute_b32 v224, v254, v198
	ds_bpermute_b32 v225, v254, v199
	ds_bpermute_b32 v222, v253, v200
	ds_bpermute_b32 v223, v253, v201
	ds_bpermute_b32 v198, v253, v198
	ds_bpermute_b32 v199, v253, v199
	ds_bpermute_b32 v200, v254, v200
	ds_bpermute_b32 v201, v254, v201
	s_waitcnt lgkmcnt(0)
	v_cndmask_b32_e32 v192, v192, v218, vcc
	v_cndmask_b32_e32 v193, v193, v219, vcc
	v_cndmask_b32_e32 v194, v220, v194, vcc
	v_cndmask_b32_e32 v195, v221, v195, vcc
	v_cndmask_b32_e32 v198, v198, v222, vcc
	v_cndmask_b32_e32 v199, v199, v223, vcc
	v_cndmask_b32_e32 v200, v224, v200, vcc
	v_cndmask_b32_e32 v201, v225, v201, vcc
	v_lshlrev_b32_e32 v226, 16, v193
	v_and_b32_e32 v227, 0xffff0000, v193
	v_and_b32_e32 v193, 0xffff0000, v192
	v_lshlrev_b32_e32 v192, 16, v192
	v_pk_add_f32 v[48:49], v[48:49], v[226:227]
	v_pk_add_f32 v[46:47], v[46:47], v[192:193]
	v_lshlrev_b32_e32 v240, 16, v195
	v_and_b32_e32 v241, 0xffff0000, v195
	v_and_b32_e32 v195, 0xffff0000, v194
	v_lshlrev_b32_e32 v194, 16, v194
	v_pk_add_f32 v[44:45], v[44:45], v[240:241]
	v_pk_add_f32 v[42:43], v[42:43], v[194:195]
	v_lshlrev_b32_e32 v226, 16, v199
	v_and_b32_e32 v227, 0xffff0000, v199
	v_and_b32_e32 v199, 0xffff0000, v198
	v_lshlrev_b32_e32 v198, 16, v198
	v_pk_add_f32 v[40:41], v[40:41], v[226:227]
	v_pk_add_f32 v[38:39], v[38:39], v[198:199]
	v_lshlrev_b32_e32 v240, 16, v201
	v_and_b32_e32 v241, 0xffff0000, v201
	v_and_b32_e32 v201, 0xffff0000, v200
	v_lshlrev_b32_e32 v200, 16, v200
	v_pk_add_f32 v[36:37], v[36:37], v[240:241]
	v_pk_add_f32 v[34:35], v[34:35], v[200:201]
	v_cvt_pk_bf16_f32 v46, v46, v47
	v_cvt_pk_bf16_f32 v47, v48, v49
	v_cvt_pk_bf16_f32 v42, v42, v43
	v_cvt_pk_bf16_f32 v43, v44, v45
	v_cvt_pk_bf16_f32 v38, v38, v39
	v_cvt_pk_bf16_f32 v39, v40, v41
	v_cvt_pk_bf16_f32 v34, v34, v35
	v_cvt_pk_bf16_f32 v35, v36, v37
	ds_bpermute_b32 v192, v244, v46
	ds_bpermute_b32 v193, v244, v47
	ds_bpermute_b32 v194, v244, v42
	ds_bpermute_b32 v195, v244, v43
	ds_bpermute_b32 v198, v245, v46
	ds_bpermute_b32 v199, v245, v47
	ds_bpermute_b32 v200, v245, v42
	ds_bpermute_b32 v201, v245, v43
	s_waitcnt lgkmcnt(0)
	v_cndmask_b32_e64 v192, v192, v194, s[98:99]
	v_cndmask_b32_e64 v193, v193, v195, s[98:99]
	v_add_u32_e32 v194, 0x48000, v246
	global_store_dwordx2 v194, v[192:193], s[8:9]
	v_cndmask_b32_e64 v198, v198, v200, s[98:99]
	v_cndmask_b32_e64 v199, v199, v201, s[98:99]
	v_add_u32_e32 v200, 0x4c000, v246
	global_store_dwordx2 v200, v[198:199], s[8:9]
	ds_bpermute_b32 v192, v244, v38
	ds_bpermute_b32 v193, v244, v39
	ds_bpermute_b32 v194, v244, v34
	ds_bpermute_b32 v195, v244, v35
	ds_bpermute_b32 v198, v245, v38
	ds_bpermute_b32 v199, v245, v39
	ds_bpermute_b32 v200, v245, v34
	ds_bpermute_b32 v201, v245, v35
	s_waitcnt lgkmcnt(0)
	v_cndmask_b32_e64 v192, v192, v194, s[98:99]
	v_cndmask_b32_e64 v193, v193, v195, s[98:99]
	v_add_u32_e32 v194, 0x48000, v246
	global_store_dwordx2 v194, v[192:193], s[8:9] offset:256
	v_cndmask_b32_e64 v198, v198, v200, s[98:99]
	v_cndmask_b32_e64 v199, v199, v201, s[98:99]
	v_add_u32_e32 v200, 0x4c000, v246
	global_store_dwordx2 v200, v[198:199], s[8:9] offset:256
	s_waitcnt vmcnt(28)
	ds_bpermute_b32 v220, v254, v202
	ds_bpermute_b32 v221, v254, v203
	ds_bpermute_b32 v218, v253, v204
	ds_bpermute_b32 v219, v253, v205
	ds_bpermute_b32 v202, v253, v202
	ds_bpermute_b32 v203, v253, v203
	ds_bpermute_b32 v204, v254, v204
	ds_bpermute_b32 v205, v254, v205
	ds_bpermute_b32 v224, v254, v206
	ds_bpermute_b32 v225, v254, v207
	ds_bpermute_b32 v222, v253, v208
	ds_bpermute_b32 v223, v253, v209
	ds_bpermute_b32 v206, v253, v206
	ds_bpermute_b32 v207, v253, v207
	ds_bpermute_b32 v208, v254, v208
	ds_bpermute_b32 v209, v254, v209
	s_waitcnt lgkmcnt(0)
	v_cndmask_b32_e32 v202, v202, v218, vcc
	v_cndmask_b32_e32 v203, v203, v219, vcc
	v_cndmask_b32_e32 v204, v220, v204, vcc
	v_cndmask_b32_e32 v205, v221, v205, vcc
	v_cndmask_b32_e32 v206, v206, v222, vcc
	v_cndmask_b32_e32 v207, v207, v223, vcc
	v_cndmask_b32_e32 v208, v224, v208, vcc
	v_cndmask_b32_e32 v209, v225, v209, vcc
	v_lshlrev_b32_e32 v226, 16, v203
	v_and_b32_e32 v227, 0xffff0000, v203
	v_and_b32_e32 v203, 0xffff0000, v202
	v_lshlrev_b32_e32 v202, 16, v202
	v_pk_add_f32 v[32:33], v[32:33], v[226:227]
	v_pk_add_f32 v[30:31], v[30:31], v[202:203]
	v_lshlrev_b32_e32 v240, 16, v205
	v_and_b32_e32 v241, 0xffff0000, v205
	v_and_b32_e32 v205, 0xffff0000, v204
	v_lshlrev_b32_e32 v204, 16, v204
	v_pk_add_f32 v[28:29], v[28:29], v[240:241]
	v_pk_add_f32 v[26:27], v[26:27], v[204:205]
	v_lshlrev_b32_e32 v226, 16, v207
	v_and_b32_e32 v227, 0xffff0000, v207
	v_and_b32_e32 v207, 0xffff0000, v206
	v_lshlrev_b32_e32 v206, 16, v206
	v_pk_add_f32 v[24:25], v[24:25], v[226:227]
	v_pk_add_f32 v[22:23], v[22:23], v[206:207]
	v_lshlrev_b32_e32 v240, 16, v209
	v_and_b32_e32 v241, 0xffff0000, v209
	v_and_b32_e32 v209, 0xffff0000, v208
	v_lshlrev_b32_e32 v208, 16, v208
	v_pk_add_f32 v[20:21], v[20:21], v[240:241]
	v_pk_add_f32 v[18:19], v[18:19], v[208:209]
	v_cvt_pk_bf16_f32 v30, v30, v31
	v_cvt_pk_bf16_f32 v31, v32, v33
	v_cvt_pk_bf16_f32 v26, v26, v27
	v_cvt_pk_bf16_f32 v27, v28, v29
	v_cvt_pk_bf16_f32 v22, v22, v23
	v_cvt_pk_bf16_f32 v23, v24, v25
	v_cvt_pk_bf16_f32 v18, v18, v19
	v_cvt_pk_bf16_f32 v19, v20, v21
	ds_bpermute_b32 v202, v244, v30
	ds_bpermute_b32 v203, v244, v31
	ds_bpermute_b32 v204, v244, v26
	ds_bpermute_b32 v205, v244, v27
	ds_bpermute_b32 v206, v245, v30
	ds_bpermute_b32 v207, v245, v31
	ds_bpermute_b32 v208, v245, v26
	ds_bpermute_b32 v209, v245, v27
	s_waitcnt lgkmcnt(0)
; DI unsigned pk_bf16(float a, float b) { f32x2 v = {a, b}; bf2_t r = __builtin_convertvector(v, bf2_t); return __builtin_bit_cast(unsigned, r); }
; DI float bflo(unsigned u) { return __uint_as_float(u << 16); }
; DI float bfhi(unsigned u) { return __uint_as_float(u & 0xffff0000u); }
;     DI void operator()(const f32x4 (&acc)[2][2][4][2], const Unit& u, int wr, int wc, int fr, int fq) const {
;         const int row0 = u.pm * BM + wr * 64 + fr, col0 = u.pn * BM + wc * 32 + 4 * fq;
; #pragma unroll
;         for (int ai = 0; ai < 2; ++ai)
; #pragma unroll
;             for (int m = 0; m < 4; ++m) { const size_t o = (size_t)(row0 + ai * HALF + m * 16) * 1024 + col0;
; #pragma unroll
;                 for (int bj = 0; bj < 2; ++bj)
; #pragma unroll
;                     for (int n = 0; n < 2; ++n) { const size_t oo = o + bj * HALF + n * 16; f32x4 rv;
;                         if (RES_BF16) { const u32x2 t = *(const u32x2*)((const bf16_t*)res + oo); rv = (f32x4){bflo(t.x), bfhi(t.x), bflo(t.y), bfhi(t.y)}; }
;                         else rv = *(const f32x4*)((const float*)res + oo);
;                         const f32x4 v = acc[ai][bj][m][n] + rv; u32x2 w; w.x = pk_bf16(v.x, v.y); w.y = pk_bf16(v.z, v.w);
;                         *(u32x2*)(O + oo) = w; } }
; template <class Epi, class Sched>
; DI void gemm_phase(LAS unsigned char* lds, const Gemm g, const Sched& S, const Epi& E) {
;     ...
;         E(acc, cur, wr, wc, fr, fq);
;         if (!has_next) break;
; #pragma unroll
;         for (int a = 0; a < 2; ++a)
; #pragma unroll
;             for (int b = 0; b < 2; ++b)
; #pragma unroll
;                 for (int m = 0; m < 4; ++m)
; #pragma unroll
;                     for (int n = 0; n < 2; ++n) acc[a][b][m][n] = (f32x4){0.f, 0.f, 0.f, 0.f};
;         cur = nxt; cA = nA; cB = nB; ++ui;
	v_cndmask_b32_e64 v202, v202, v204, s[98:99]
	v_cndmask_b32_e64 v203, v203, v205, s[98:99]
	v_add_u32_e32 v204, 0x50000, v246
	global_store_dwordx2 v204, v[202:203], s[8:9]
	v_cndmask_b32_e64 v206, v206, v208, s[98:99]
	v_cndmask_b32_e64 v207, v207, v209, s[98:99]
	v_add_u32_e32 v208, 0x54000, v246
	global_store_dwordx2 v208, v[206:207], s[8:9]
	ds_bpermute_b32 v202, v244, v22
	ds_bpermute_b32 v203, v244, v23
	ds_bpermute_b32 v204, v244, v18
	ds_bpermute_b32 v205, v244, v19
	ds_bpermute_b32 v206, v245, v22
	ds_bpermute_b32 v207, v245, v23
	ds_bpermute_b32 v208, v245, v18
	ds_bpermute_b32 v209, v245, v19
	s_waitcnt lgkmcnt(0)
	v_cndmask_b32_e64 v202, v202, v204, s[98:99]
	v_cndmask_b32_e64 v203, v203, v205, s[98:99]
	v_add_u32_e32 v204, 0x50000, v246
	global_store_dwordx2 v204, v[202:203], s[8:9] offset:256
	v_cndmask_b32_e64 v206, v206, v208, s[98:99]
	v_cndmask_b32_e64 v207, v207, v209, s[98:99]
	v_add_u32_e32 v208, 0x54000, v246
	global_store_dwordx2 v208, v[206:207], s[8:9] offset:256
	s_waitcnt vmcnt(28)
	ds_bpermute_b32 v220, v254, v210
	ds_bpermute_b32 v221, v254, v211
	ds_bpermute_b32 v218, v253, v212
	ds_bpermute_b32 v219, v253, v213
	ds_bpermute_b32 v210, v253, v210
	ds_bpermute_b32 v211, v253, v211
	ds_bpermute_b32 v212, v254, v212
	ds_bpermute_b32 v213, v254, v213
	ds_bpermute_b32 v224, v254, v214
	ds_bpermute_b32 v225, v254, v215
	ds_bpermute_b32 v222, v253, v216
	ds_bpermute_b32 v223, v253, v217
	ds_bpermute_b32 v214, v253, v214
	ds_bpermute_b32 v215, v253, v215
	ds_bpermute_b32 v216, v254, v216
	ds_bpermute_b32 v217, v254, v217
	s_waitcnt lgkmcnt(0)
	v_cndmask_b32_e32 v210, v210, v218, vcc
	v_cndmask_b32_e32 v211, v211, v219, vcc
	v_cndmask_b32_e32 v212, v220, v212, vcc
	v_cndmask_b32_e32 v213, v221, v213, vcc
	v_cndmask_b32_e32 v214, v214, v222, vcc
	v_cndmask_b32_e32 v215, v215, v223, vcc
	v_cndmask_b32_e32 v216, v224, v216, vcc
	v_cndmask_b32_e32 v217, v225, v217, vcc
	v_lshlrev_b32_e32 v226, 16, v211
	v_and_b32_e32 v227, 0xffff0000, v211
	v_and_b32_e32 v211, 0xffff0000, v210
	v_lshlrev_b32_e32 v210, 16, v210
	v_pk_add_f32 v[16:17], v[16:17], v[226:227]
	v_pk_add_f32 v[14:15], v[14:15], v[210:211]
	v_lshlrev_b32_e32 v240, 16, v213
	v_and_b32_e32 v241, 0xffff0000, v213
	v_and_b32_e32 v213, 0xffff0000, v212
	v_lshlrev_b32_e32 v212, 16, v212
	v_pk_add_f32 v[12:13], v[12:13], v[240:241]
	v_pk_add_f32 v[10:11], v[10:11], v[212:213]
	v_lshlrev_b32_e32 v226, 16, v215
	v_and_b32_e32 v227, 0xffff0000, v215
	v_and_b32_e32 v215, 0xffff0000, v214
	v_lshlrev_b32_e32 v214, 16, v214
	v_pk_add_f32 v[8:9], v[8:9], v[226:227]
	v_pk_add_f32 v[6:7], v[6:7], v[214:215]
	v_lshlrev_b32_e32 v240, 16, v217
	v_and_b32_e32 v241, 0xffff0000, v217
	v_and_b32_e32 v217, 0xffff0000, v216
	v_lshlrev_b32_e32 v216, 16, v216
	v_pk_add_f32 v[4:5], v[4:5], v[240:241]
	v_pk_add_f32 v[2:3], v[2:3], v[216:217]
	v_cvt_pk_bf16_f32 v14, v14, v15
	v_cvt_pk_bf16_f32 v15, v16, v17
	v_cvt_pk_bf16_f32 v10, v10, v11
	v_cvt_pk_bf16_f32 v11, v12, v13
	v_cvt_pk_bf16_f32 v6, v6, v7
	v_cvt_pk_bf16_f32 v7, v8, v9
	v_cvt_pk_bf16_f32 v2, v2, v3
	v_cvt_pk_bf16_f32 v3, v4, v5
	ds_bpermute_b32 v210, v244, v14
	ds_bpermute_b32 v211, v244, v15
	ds_bpermute_b32 v212, v244, v10
	ds_bpermute_b32 v213, v244, v11
	ds_bpermute_b32 v214, v245, v14
	ds_bpermute_b32 v215, v245, v15
	ds_bpermute_b32 v216, v245, v10
	ds_bpermute_b32 v217, v245, v11
	s_waitcnt lgkmcnt(0)
	v_cndmask_b32_e64 v210, v210, v212, s[98:99]
	v_cndmask_b32_e64 v211, v211, v213, s[98:99]
	v_add_u32_e32 v212, 0x58000, v246
	global_store_dwordx2 v212, v[210:211], s[8:9]
	v_cndmask_b32_e64 v214, v214, v216, s[98:99]
	v_cndmask_b32_e64 v215, v215, v217, s[98:99]
	v_add_u32_e32 v216, 0x5c000, v246
	global_store_dwordx2 v216, v[214:215], s[8:9]
	ds_bpermute_b32 v210, v244, v6
	ds_bpermute_b32 v211, v244, v7
	ds_bpermute_b32 v212, v244, v2
	ds_bpermute_b32 v213, v244, v3
	ds_bpermute_b32 v214, v245, v6
	ds_bpermute_b32 v215, v245, v7
	ds_bpermute_b32 v216, v245, v2
	ds_bpermute_b32 v217, v245, v3
	s_waitcnt lgkmcnt(0)
	v_cndmask_b32_e64 v210, v210, v212, s[98:99]
	v_cndmask_b32_e64 v211, v211, v213, s[98:99]
	v_add_u32_e32 v212, 0x58000, v246
	global_store_dwordx2 v212, v[210:211], s[8:9] offset:256
	v_cndmask_b32_e64 v214, v214, v216, s[98:99]
	v_cndmask_b32_e64 v215, v215, v217, s[98:99]
	v_add_u32_e32 v216, 0x5c000, v246
	global_store_dwordx2 v216, v[214:215], s[8:9] offset:256
	s_and_b64 vcc, exec, s[40:41]
	s_mov_b32 s84, s65
	s_mov_b32 s56, s66
	s_cbranch_vccz .LBB0_1522
	s_waitcnt vmcnt(0)
	s_cmpk_gt_u32 s3, 0xff
	s_cbranch_scc1 .LBB0_1527
	s_barrier
